# speedup vs baseline: 1.0115x; 1.0022x over previous
;     DI size_t aoff(const Unit& u, size_t tstep) const { return (size_t)u.pm * tstep; }
;     DI size_t boff(const Unit& u, size_t tstep) const { return (size_t)u.pn * tstep; }
;     DI bool next(int i, Unit& u) const { const long L = (long)i * G + c; if (L >= np) return false; u.pm = pmv; u.pn = (int)(L % nN); u.ks = (int)(L / nN); return true; }
;     DI size_t aoff(const Unit& u, size_t) const { return (size_t)u.ks * kbytes; }
;     DI size_t boff(const Unit& u, size_t tstep) const { return (size_t)u.pn * tstep + (size_t)u.ks * kbytes; }
;     DI bool next(int i, Unit& u) const { Unit t; if (!S.next(i / 3, t)) return false; u.pm = t.pm; u.pn = t.pn; u.ks = i % 3; return true; }
;     DI size_t aoff(const Unit& u, size_t tstep) const { return (u.ks < 2 ? offU : offOA) + (size_t)u.pm * tstep; }
; template <class Epi, class Sched>
; DI void gemm_phase(LAS unsigned char* lds, const Gemm g, const Sched& S, const Epi& E) {
;     ...
;         const bool has_next = S.next(ui + 1, nxt);
;         const char* nA = has_next ? (const char*)g.A + S.aoff(nxt, tstep) : cA; const char* nB = has_next ? (const char*)g.Bt + S.boff(nxt, tstep) : cB;
;         for (int t = 0; t < nt; t += 2) {
;             if constexpr (Epi::HAS_MID) { if (t == E.mid_t(nt)) { int fr3 = fr, fq3 = fq; asm volatile("" : "+v"(fr3), "+v"(fq3)); E.mid(acc, cur, wr, wc, fr3, fq3); } }
;             const bool last = (t == nt - 2);
;             const char* a1 = cA + (size_t)(t + 1) * kstep;
;             const char* a2 = last ? nA : cA + (size_t)(t + 2) * kstep; const char* b2 = last ? nB : cB + (size_t)(t + 2) * kstep;
;             const char* a3 = a2 + kstep; const char* b3 = b2 + kstep;
;     ...
;         for (int a = 0; a < 2; ++a)
; #pragma unroll
;             for (int b = 0; b < 2; ++b)
; #pragma unroll
;                 for (int m = 0; m < 4; ++m)
; #pragma unroll
;                     for (int n = 0; n < 2; ++n) acc[a][b][m][n] = (f32x4){0.f, 0.f, 0.f, 0.f};
.LBB0_218:
	s_ashr_i32 s17, s16, 31
	s_lshl_b64 s[0:1], s[16:17], 20
	v_cmp_lt_i64_e32 vcc, s[18:19], v[140:141]
	s_add_u32 s18, s47, s0
	s_addc_u32 s19, s48, s1
	s_and_b64 s[0:1], vcc, exec
	s_cselect_b32 s17, s19, s41
	s_cselect_b32 s65, s18, s40
	s_ashr_i32 s15, s14, 31
	s_lshl_b64 s[0:1], s[14:15], 20
	s_add_u32 s36, s49, s0
	s_addc_u32 s37, s50, s1
	s_and_b64 s[0:1], vcc, exec
	s_cselect_b32 s15, s37, s43
	s_cselect_b32 s66, s36, s42
	s_add_u32 s40, s40, 0x80080
	s_addc_u32 s41, s41, 0
	s_add_u32 s67, s42, 0x100
	v_mov_b32_e32 v0, 0
	s_addc_u32 s68, s43, 0
	s_mov_b32 s69, -2
	v_mov_b32_e32 v1, 0
	v_mov_b64_e32 v[2:3], 0
	v_mov_b64_e32 v[4:5], 0
	v_mov_b64_e32 v[6:7], 0
	v_mov_b64_e32 v[8:9], 0
	v_mov_b64_e32 v[10:11], 0
	v_mov_b64_e32 v[12:13], 0
	v_mov_b64_e32 v[14:15], 0
	v_mov_b64_e32 v[16:17], 0
	v_mov_b64_e32 v[18:19], 0
	v_mov_b64_e32 v[20:21], 0
	v_mov_b64_e32 v[22:23], 0
	v_mov_b64_e32 v[24:25], 0
	v_mov_b64_e32 v[26:27], 0
	v_mov_b64_e32 v[28:29], 0
	v_mov_b64_e32 v[30:31], 0
	v_mov_b64_e32 v[32:33], 0
	v_mov_b64_e32 v[34:35], 0
	v_mov_b64_e32 v[36:37], 0
	v_mov_b64_e32 v[38:39], 0
	v_mov_b64_e32 v[40:41], 0
	v_mov_b64_e32 v[42:43], 0
	v_mov_b64_e32 v[44:45], 0
	v_mov_b64_e32 v[46:47], 0
	v_mov_b64_e32 v[48:49], 0
	v_mov_b64_e32 v[50:51], 0
	v_mov_b64_e32 v[52:53], 0
	v_mov_b64_e32 v[54:55], 0
	v_mov_b64_e32 v[56:57], 0
	v_mov_b64_e32 v[58:59], 0
	v_mov_b64_e32 v[60:61], 0
	v_mov_b64_e32 v[62:63], 0
	v_mov_b64_e32 v[64:65], 0
	v_mov_b64_e32 v[66:67], 0
	v_mov_b64_e32 v[68:69], 0
	v_mov_b64_e32 v[70:71], 0
	v_mov_b64_e32 v[72:73], 0
	v_mov_b64_e32 v[74:75], 0
	v_mov_b64_e32 v[76:77], 0
	v_mov_b64_e32 v[78:79], 0
	v_mov_b64_e32 v[80:81], 0
	v_mov_b64_e32 v[82:83], 0
	v_mov_b64_e32 v[84:85], 0
	v_mov_b64_e32 v[86:87], 0
	v_mov_b64_e32 v[88:89], 0
	v_mov_b64_e32 v[90:91], 0
	v_mov_b64_e32 v[92:93], 0
	v_mov_b64_e32 v[94:95], 0
	v_mov_b64_e32 v[96:97], 0
	v_mov_b64_e32 v[98:99], 0
	v_mov_b64_e32 v[100:101], 0
	v_mov_b64_e32 v[102:103], 0
	v_mov_b64_e32 v[104:105], 0
	v_mov_b64_e32 v[106:107], 0
	v_mov_b64_e32 v[108:109], 0
	v_mov_b64_e32 v[110:111], 0
	v_mov_b64_e32 v[112:113], 0
	v_mov_b64_e32 v[114:115], 0
	v_mov_b64_e32 v[116:117], 0
	v_mov_b64_e32 v[118:119], 0
	v_mov_b64_e32 v[120:121], 0
	v_mov_b64_e32 v[122:123], 0
	v_mov_b64_e32 v[124:125], 0
	v_mov_b64_e32 v[126:127], 0

;     DI size_t aoff(const Unit& u, size_t tstep) const { return (size_t)u.pm * tstep; }
;     DI size_t boff(const Unit& u, size_t tstep) const { return (size_t)u.pn * tstep; }
;     DI bool next(int i, Unit& u) const { const long L = (long)i * G + c; if (L >= np) return false; u.pm = pmv; u.pn = (int)(L % nN); u.ks = (int)(L / nN); return true; }
;     DI size_t aoff(const Unit& u, size_t) const { return (size_t)u.ks * kbytes; }
;     DI size_t boff(const Unit& u, size_t tstep) const { return (size_t)u.pn * tstep + (size_t)u.ks * kbytes; }
;     DI bool next(int i, Unit& u) const { Unit t; if (!S.next(i / 3, t)) return false; u.pm = t.pm; u.pn = t.pn; u.ks = i % 3; return true; }
;     DI size_t aoff(const Unit& u, size_t tstep) const { return (u.ks < 2 ? offU : offOA) + (size_t)u.pm * tstep; }
; template <class Epi, class Sched>
; DI void gemm_phase(LAS unsigned char* lds, const Gemm g, const Sched& S, const Epi& E) {
;     ...
;         const bool has_next = S.next(ui + 1, nxt);
;         const char* nA = has_next ? (const char*)g.A + S.aoff(nxt, tstep) : cA; const char* nB = has_next ? (const char*)g.Bt + S.boff(nxt, tstep) : cB;
;         for (int t = 0; t < nt; t += 2) {
;             if constexpr (Epi::HAS_MID) { if (t == E.mid_t(nt)) { int fr3 = fr, fq3 = fq; asm volatile("" : "+v"(fr3), "+v"(fq3)); E.mid(acc, cur, wr, wc, fr3, fq3); } }
;             const bool last = (t == nt - 2);
;             const char* a1 = cA + (size_t)(t + 1) * kstep;
;             const char* a2 = last ? nA : cA + (size_t)(t + 2) * kstep; const char* b2 = last ? nB : cB + (size_t)(t + 2) * kstep;
;             const char* a3 = a2 + kstep; const char* b3 = b2 + kstep;
;     ...
;         for (int a = 0; a < 2; ++a)
; #pragma unroll
;             for (int b = 0; b < 2; ++b)
; #pragma unroll
;                 for (int m = 0; m < 4; ++m)
; #pragma unroll
;                     for (int n = 0; n < 2; ++n) acc[a][b][m][n] = (f32x4){0.f, 0.f, 0.f, 0.f};
.LBB0_296:
	s_add_u32 s40, s40, 0x160080
	s_addc_u32 s41, s41, 0
	s_add_u32 s35, s42, 0x100
	v_mov_b32_e32 v0, 0
	s_addc_u32 s68, s43, 0
	s_mov_b32 s69, -2
	s_waitcnt lgkmcnt(0)
	v_mov_b32_e32 v1, 0
	v_mov_b64_e32 v[2:3], 0
	v_mov_b64_e32 v[4:5], 0
	v_mov_b64_e32 v[6:7], 0
	v_mov_b64_e32 v[8:9], 0
	v_mov_b64_e32 v[10:11], 0
	v_mov_b64_e32 v[12:13], 0
	v_mov_b64_e32 v[14:15], 0
	v_mov_b64_e32 v[16:17], 0
	v_mov_b64_e32 v[18:19], 0
	v_mov_b64_e32 v[20:21], 0
	v_mov_b64_e32 v[22:23], 0
	v_mov_b64_e32 v[24:25], 0
	v_mov_b64_e32 v[26:27], 0
	v_mov_b64_e32 v[28:29], 0
	v_mov_b64_e32 v[30:31], 0
	v_mov_b64_e32 v[32:33], 0
	v_mov_b64_e32 v[34:35], 0
	v_mov_b64_e32 v[36:37], 0
	v_mov_b64_e32 v[38:39], 0
	v_mov_b64_e32 v[40:41], 0
	v_mov_b64_e32 v[42:43], 0
	v_mov_b64_e32 v[44:45], 0
	v_mov_b64_e32 v[46:47], 0
	v_mov_b64_e32 v[48:49], 0
	v_mov_b64_e32 v[50:51], 0
	v_mov_b64_e32 v[52:53], 0
	v_mov_b64_e32 v[54:55], 0
	v_mov_b64_e32 v[56:57], 0
	v_mov_b64_e32 v[58:59], 0
	v_mov_b64_e32 v[60:61], 0
	v_mov_b64_e32 v[62:63], 0
	v_mov_b64_e32 v[64:65], 0
	v_mov_b64_e32 v[66:67], 0
	v_mov_b64_e32 v[68:69], 0
	v_mov_b64_e32 v[70:71], 0
	v_mov_b64_e32 v[72:73], 0
	v_mov_b64_e32 v[74:75], 0
	v_mov_b64_e32 v[76:77], 0
	v_mov_b64_e32 v[78:79], 0
	v_mov_b64_e32 v[80:81], 0
	v_mov_b64_e32 v[82:83], 0
	v_mov_b64_e32 v[84:85], 0
	v_mov_b64_e32 v[86:87], 0
	v_mov_b64_e32 v[88:89], 0
	v_mov_b64_e32 v[90:91], 0
	v_mov_b64_e32 v[92:93], 0
	v_mov_b64_e32 v[94:95], 0
	v_mov_b64_e32 v[96:97], 0
	v_mov_b64_e32 v[98:99], 0
	v_mov_b64_e32 v[100:101], 0
	v_mov_b64_e32 v[102:103], 0
	v_mov_b64_e32 v[104:105], 0
	v_mov_b64_e32 v[106:107], 0
	v_mov_b64_e32 v[108:109], 0
	v_mov_b64_e32 v[110:111], 0
	v_mov_b64_e32 v[112:113], 0
	v_mov_b64_e32 v[114:115], 0
	v_mov_b64_e32 v[116:117], 0
	v_mov_b64_e32 v[118:119], 0
	v_mov_b64_e32 v[120:121], 0
	v_mov_b64_e32 v[122:123], 0
	v_mov_b64_e32 v[124:125], 0
	v_mov_b64_e32 v[126:127], 0

;     DI size_t aoff(const Unit& u, size_t tstep) const { return (size_t)u.pm * tstep; }
;     DI size_t boff(const Unit& u, size_t tstep) const { return (size_t)u.pn * tstep; }
;     DI bool next(int i, Unit& u) const { const long L = (long)i * G + c; if (L >= np) return false; u.pm = pmv; u.pn = (int)(L % nN); u.ks = (int)(L / nN); return true; }
;     DI size_t aoff(const Unit& u, size_t) const { return (size_t)u.ks * kbytes; }
;     DI size_t boff(const Unit& u, size_t tstep) const { return (size_t)u.pn * tstep + (size_t)u.ks * kbytes; }
;     DI bool next(int i, Unit& u) const { Unit t; if (!S.next(i / 3, t)) return false; u.pm = t.pm; u.pn = t.pn; u.ks = i % 3; return true; }
;     DI size_t aoff(const Unit& u, size_t tstep) const { return (u.ks < 2 ? offU : offOA) + (size_t)u.pm * tstep; }
; template <class Epi, class Sched>
; DI void gemm_phase(LAS unsigned char* lds, const Gemm g, const Sched& S, const Epi& E) {
;     ...
;         const bool has_next = S.next(ui + 1, nxt);
;         const char* nA = has_next ? (const char*)g.A + S.aoff(nxt, tstep) : cA; const char* nB = has_next ? (const char*)g.Bt + S.boff(nxt, tstep) : cB;
;         for (int t = 0; t < nt; t += 2) {
;             if constexpr (Epi::HAS_MID) { if (t == E.mid_t(nt)) { int fr3 = fr, fq3 = fq; asm volatile("" : "+v"(fr3), "+v"(fq3)); E.mid(acc, cur, wr, wc, fr3, fq3); } }
;             const bool last = (t == nt - 2);
;             const char* a1 = cA + (size_t)(t + 1) * kstep;
;             const char* a2 = last ? nA : cA + (size_t)(t + 2) * kstep; const char* b2 = last ? nB : cB + (size_t)(t + 2) * kstep;
;             const char* a3 = a2 + kstep; const char* b3 = b2 + kstep;
;     ...
;         for (int a = 0; a < 2; ++a)
; #pragma unroll
;             for (int b = 0; b < 2; ++b)
; #pragma unroll
;                 for (int m = 0; m < 4; ++m)
; #pragma unroll
;                     for (int n = 0; n < 2; ++n) acc[a][b][m][n] = (f32x4){0.f, 0.f, 0.f, 0.f};
.LBB0_325:
	s_add_u32 s28, s40, s28
	s_addc_u32 s29, s41, s29
	s_and_b64 s[0:1], s[8:9], exec
	s_cselect_b32 s15, s29, s39
	s_cselect_b32 s17, s28, s38
	s_add_u32 s8, s38, 0x160080
	s_addc_u32 s9, s39, 0
	s_add_u32 s66, s36, 0x100
	v_mov_b32_e32 v0, 0
	s_addc_u32 s67, s37, 0
	s_mov_b32 s68, -2
	v_mov_b32_e32 v1, 0
	v_mov_b64_e32 v[2:3], 0
	v_mov_b64_e32 v[4:5], 0
	v_mov_b64_e32 v[6:7], 0
	v_mov_b64_e32 v[8:9], 0
	v_mov_b64_e32 v[10:11], 0
	v_mov_b64_e32 v[12:13], 0
	v_mov_b64_e32 v[14:15], 0
	v_mov_b64_e32 v[16:17], 0
	v_mov_b64_e32 v[18:19], 0
	v_mov_b64_e32 v[20:21], 0
	v_mov_b64_e32 v[22:23], 0
	v_mov_b64_e32 v[24:25], 0
	v_mov_b64_e32 v[26:27], 0
	v_mov_b64_e32 v[28:29], 0
	v_mov_b64_e32 v[30:31], 0
	v_mov_b64_e32 v[32:33], 0
	v_mov_b64_e32 v[34:35], 0
	v_mov_b64_e32 v[36:37], 0
	v_mov_b64_e32 v[38:39], 0
	v_mov_b64_e32 v[40:41], 0
	v_mov_b64_e32 v[42:43], 0
	v_mov_b64_e32 v[44:45], 0
	v_mov_b64_e32 v[46:47], 0
	v_mov_b64_e32 v[48:49], 0
	v_mov_b64_e32 v[50:51], 0
	v_mov_b64_e32 v[52:53], 0
	v_mov_b64_e32 v[54:55], 0
	v_mov_b64_e32 v[56:57], 0
	v_mov_b64_e32 v[58:59], 0
	v_mov_b64_e32 v[60:61], 0
	v_mov_b64_e32 v[62:63], 0
	v_mov_b64_e32 v[64:65], 0
	v_mov_b64_e32 v[66:67], 0
	v_mov_b64_e32 v[68:69], 0
	v_mov_b64_e32 v[70:71], 0
	v_mov_b64_e32 v[72:73], 0
	v_mov_b64_e32 v[74:75], 0
	v_mov_b64_e32 v[76:77], 0
	v_mov_b64_e32 v[78:79], 0
	v_mov_b64_e32 v[80:81], 0
	v_mov_b64_e32 v[82:83], 0
	v_mov_b64_e32 v[84:85], 0
	v_mov_b64_e32 v[86:87], 0
	v_mov_b64_e32 v[88:89], 0
	v_mov_b64_e32 v[90:91], 0
	v_mov_b64_e32 v[92:93], 0
	v_mov_b64_e32 v[94:95], 0
	v_mov_b64_e32 v[96:97], 0
	v_mov_b64_e32 v[98:99], 0
	v_mov_b64_e32 v[100:101], 0
	v_mov_b64_e32 v[102:103], 0
	v_mov_b64_e32 v[104:105], 0
	v_mov_b64_e32 v[106:107], 0
	v_mov_b64_e32 v[108:109], 0
	v_mov_b64_e32 v[110:111], 0
	v_mov_b64_e32 v[112:113], 0
	v_mov_b64_e32 v[114:115], 0
	v_mov_b64_e32 v[116:117], 0
	v_mov_b64_e32 v[118:119], 0
	v_mov_b64_e32 v[120:121], 0
	v_mov_b64_e32 v[122:123], 0
	v_mov_b64_e32 v[124:125], 0
	v_mov_b64_e32 v[126:127], 0

;     DI size_t aoff(const Unit& u, size_t tstep) const { return (size_t)u.pm * tstep; }
;     DI size_t boff(const Unit& u, size_t tstep) const { return (size_t)u.pn * tstep; }
;     DI bool next(int i, Unit& u) const { const long L = (long)i * G + c; if (L >= np) return false; u.pm = pmv; u.pn = (int)(L % nN); u.ks = (int)(L / nN); return true; }
;     DI size_t aoff(const Unit& u, size_t) const { return (size_t)u.ks * kbytes; }
;     DI size_t boff(const Unit& u, size_t tstep) const { return (size_t)u.pn * tstep + (size_t)u.ks * kbytes; }
;     DI bool next(int i, Unit& u) const { Unit t; if (!S.next(i / 3, t)) return false; u.pm = t.pm; u.pn = t.pn; u.ks = i % 3; return true; }
;     DI size_t aoff(const Unit& u, size_t tstep) const { return (u.ks < 2 ? offU : offOA) + (size_t)u.pm * tstep; }
; template <class Epi, class Sched>
; DI void gemm_phase(LAS unsigned char* lds, const Gemm g, const Sched& S, const Epi& E) {
;     ...
;         const bool has_next = S.next(ui + 1, nxt);
;         const char* nA = has_next ? (const char*)g.A + S.aoff(nxt, tstep) : cA; const char* nB = has_next ? (const char*)g.Bt + S.boff(nxt, tstep) : cB;
;         for (int t = 0; t < nt; t += 2) {
;             if constexpr (Epi::HAS_MID) { if (t == E.mid_t(nt)) { int fr3 = fr, fq3 = fq; asm volatile("" : "+v"(fr3), "+v"(fq3)); E.mid(acc, cur, wr, wc, fr3, fq3); } }
;             const bool last = (t == nt - 2);
;             const char* a1 = cA + (size_t)(t + 1) * kstep;
;             const char* a2 = last ? nA : cA + (size_t)(t + 2) * kstep; const char* b2 = last ? nB : cB + (size_t)(t + 2) * kstep;
;             const char* a3 = a2 + kstep; const char* b3 = b2 + kstep;
;     ...
;         for (int a = 0; a < 2; ++a)
; #pragma unroll
;             for (int b = 0; b < 2; ++b)
; #pragma unroll
;                 for (int m = 0; m < 4; ++m)
; #pragma unroll
;                     for (int n = 0; n < 2; ++n) acc[a][b][m][n] = (f32x4){0.f, 0.f, 0.f, 0.f};
.LBB0_526:
	s_ashr_i32 s51, s50, 31
	s_lshl_b64 s[0:1], s[50:51], 20
	s_add_u32 s52, s70, s0
	v_cmp_lt_i64_e32 vcc, s[12:13], v[142:143]
	s_addc_u32 s53, s71, s1
	s_and_b64 s[0:1], vcc, exec
	s_cselect_b32 s14, s53, s9
	s_cselect_b32 s15, s52, s8
	s_ashr_i32 s49, s48, 31
	s_lshl_b64 s[0:1], s[48:49], 20
	s_add_u32 s54, s72, s0
	s_addc_u32 s55, s73, s1
	s_and_b64 s[0:1], vcc, exec
	s_cselect_b32 s16, s55, s11
	s_cselect_b32 s17, s54, s10
	s_add_u32 s8, s8, 0x80080
	s_addc_u32 s9, s9, 0
	s_add_u32 s28, s10, 0x100
	v_mov_b32_e32 v0, 0
	s_addc_u32 s34, s11, 0
	s_mov_b32 s35, -2
	v_mov_b32_e32 v1, 0
	v_mov_b64_e32 v[2:3], 0
	v_mov_b64_e32 v[4:5], 0
	v_mov_b64_e32 v[6:7], 0
	v_mov_b64_e32 v[8:9], 0
	v_mov_b64_e32 v[10:11], 0
	v_mov_b64_e32 v[12:13], 0
	v_mov_b64_e32 v[14:15], 0
	v_mov_b64_e32 v[16:17], 0
	v_mov_b64_e32 v[18:19], 0
	v_mov_b64_e32 v[20:21], 0
	v_mov_b64_e32 v[22:23], 0
	v_mov_b64_e32 v[24:25], 0
	v_mov_b64_e32 v[26:27], 0
	v_mov_b64_e32 v[28:29], 0
	v_mov_b64_e32 v[30:31], 0
	v_mov_b64_e32 v[32:33], 0
	v_mov_b64_e32 v[34:35], 0
	v_mov_b64_e32 v[36:37], 0
	v_mov_b64_e32 v[38:39], 0
	v_mov_b64_e32 v[40:41], 0
	v_mov_b64_e32 v[42:43], 0
	v_mov_b64_e32 v[44:45], 0
	v_mov_b64_e32 v[46:47], 0
	v_mov_b64_e32 v[48:49], 0
	v_mov_b64_e32 v[50:51], 0
	v_mov_b64_e32 v[52:53], 0
	v_mov_b64_e32 v[54:55], 0
	v_mov_b64_e32 v[56:57], 0
	v_mov_b64_e32 v[58:59], 0
	v_mov_b64_e32 v[60:61], 0
	v_mov_b64_e32 v[62:63], 0
	v_mov_b64_e32 v[64:65], 0
	v_mov_b64_e32 v[66:67], 0
	v_mov_b64_e32 v[68:69], 0
	v_mov_b64_e32 v[70:71], 0
	v_mov_b64_e32 v[72:73], 0
	v_mov_b64_e32 v[74:75], 0
	v_mov_b64_e32 v[76:77], 0
	v_mov_b64_e32 v[78:79], 0
	v_mov_b64_e32 v[80:81], 0
	v_mov_b64_e32 v[82:83], 0
	v_mov_b64_e32 v[84:85], 0
	v_mov_b64_e32 v[86:87], 0
	v_mov_b64_e32 v[88:89], 0
	v_mov_b64_e32 v[90:91], 0
	v_mov_b64_e32 v[92:93], 0
	v_mov_b64_e32 v[94:95], 0
	v_mov_b64_e32 v[96:97], 0
	v_mov_b64_e32 v[98:99], 0
	v_mov_b64_e32 v[100:101], 0
	v_mov_b64_e32 v[102:103], 0
	v_mov_b64_e32 v[104:105], 0
	v_mov_b64_e32 v[106:107], 0
	v_mov_b64_e32 v[108:109], 0
	v_mov_b64_e32 v[110:111], 0
	v_mov_b64_e32 v[112:113], 0
	v_mov_b64_e32 v[114:115], 0
	v_mov_b64_e32 v[116:117], 0
	v_mov_b64_e32 v[118:119], 0
	v_mov_b64_e32 v[120:121], 0
	v_mov_b64_e32 v[122:123], 0
	v_mov_b64_e32 v[124:125], 0
	v_mov_b64_e32 v[126:127], 0

;     DI size_t aoff(const Unit& u, size_t tstep) const { return (size_t)u.pm * tstep; }
;     DI size_t boff(const Unit& u, size_t tstep) const { return (size_t)u.pn * tstep; }
;     DI bool next(int i, Unit& u) const { const long L = (long)i * G + c; if (L >= np) return false; u.pm = pmv; u.pn = (int)(L % nN); u.ks = (int)(L / nN); return true; }
;     DI size_t aoff(const Unit& u, size_t) const { return (size_t)u.ks * kbytes; }
;     DI size_t boff(const Unit& u, size_t tstep) const { return (size_t)u.pn * tstep + (size_t)u.ks * kbytes; }
;     DI bool next(int i, Unit& u) const { Unit t; if (!S.next(i / 3, t)) return false; u.pm = t.pm; u.pn = t.pn; u.ks = i % 3; return true; }
;     DI size_t aoff(const Unit& u, size_t tstep) const { return (u.ks < 2 ? offU : offOA) + (size_t)u.pm * tstep; }
; template <class Epi, class Sched>
; DI void gemm_phase(LAS unsigned char* lds, const Gemm g, const Sched& S, const Epi& E) {
;     ...
;         const bool has_next = S.next(ui + 1, nxt);
;         const char* nA = has_next ? (const char*)g.A + S.aoff(nxt, tstep) : cA; const char* nB = has_next ? (const char*)g.Bt + S.boff(nxt, tstep) : cB;
;         for (int t = 0; t < nt; t += 2) {
;             if constexpr (Epi::HAS_MID) { if (t == E.mid_t(nt)) { int fr3 = fr, fq3 = fq; asm volatile("" : "+v"(fr3), "+v"(fq3)); E.mid(acc, cur, wr, wc, fr3, fq3); } }
;             const bool last = (t == nt - 2);
;             const char* a1 = cA + (size_t)(t + 1) * kstep;
;             const char* a2 = last ? nA : cA + (size_t)(t + 2) * kstep; const char* b2 = last ? nB : cB + (size_t)(t + 2) * kstep;
;             const char* a3 = a2 + kstep; const char* b3 = b2 + kstep;
;     ...
;         for (int a = 0; a < 2; ++a)
; #pragma unroll
;             for (int b = 0; b < 2; ++b)
; #pragma unroll
;                 for (int m = 0; m < 4; ++m)
; #pragma unroll
;                     for (int n = 0; n < 2; ++n) acc[a][b][m][n] = (f32x4){0.f, 0.f, 0.f, 0.f};
.LBB0_937:
	s_add_u32 s8, s38, 0x30080
	s_addc_u32 s9, s39, 0
	s_add_u32 s35, s36, 0x100
	v_mov_b32_e32 v0, 0
	s_addc_u32 s40, s37, 0
	s_mov_b32 s41, -2
	v_mov_b32_e32 v1, 0
	v_mov_b64_e32 v[2:3], 0
	v_mov_b64_e32 v[4:5], 0
	v_mov_b64_e32 v[6:7], 0
	v_mov_b64_e32 v[8:9], 0
	v_mov_b64_e32 v[10:11], 0
	v_mov_b64_e32 v[12:13], 0
	v_mov_b64_e32 v[14:15], 0
	v_mov_b64_e32 v[16:17], 0
	v_mov_b64_e32 v[18:19], 0
	v_mov_b64_e32 v[20:21], 0
	v_mov_b64_e32 v[22:23], 0
	v_mov_b64_e32 v[24:25], 0
	v_mov_b64_e32 v[26:27], 0
	v_mov_b64_e32 v[28:29], 0
	v_mov_b64_e32 v[30:31], 0
	v_mov_b64_e32 v[32:33], 0
	v_mov_b64_e32 v[34:35], 0
	v_mov_b64_e32 v[36:37], 0
	v_mov_b64_e32 v[38:39], 0
	v_mov_b64_e32 v[40:41], 0
	v_mov_b64_e32 v[42:43], 0
	v_mov_b64_e32 v[44:45], 0
	v_mov_b64_e32 v[46:47], 0
	v_mov_b64_e32 v[48:49], 0
	v_mov_b64_e32 v[50:51], 0
	v_mov_b64_e32 v[52:53], 0
	v_mov_b64_e32 v[54:55], 0
	v_mov_b64_e32 v[56:57], 0
	v_mov_b64_e32 v[58:59], 0
	v_mov_b64_e32 v[60:61], 0
	v_mov_b64_e32 v[62:63], 0
	v_mov_b64_e32 v[64:65], 0
	v_mov_b64_e32 v[66:67], 0
	v_mov_b64_e32 v[68:69], 0
	v_mov_b64_e32 v[70:71], 0
	v_mov_b64_e32 v[72:73], 0
	v_mov_b64_e32 v[74:75], 0
	v_mov_b64_e32 v[76:77], 0
	v_mov_b64_e32 v[78:79], 0
	v_mov_b64_e32 v[80:81], 0
	v_mov_b64_e32 v[82:83], 0
	v_mov_b64_e32 v[84:85], 0
	v_mov_b64_e32 v[86:87], 0
	v_mov_b64_e32 v[88:89], 0
	v_mov_b64_e32 v[90:91], 0
	v_mov_b64_e32 v[92:93], 0
	v_mov_b64_e32 v[94:95], 0
	v_mov_b64_e32 v[96:97], 0
	v_mov_b64_e32 v[98:99], 0
	v_mov_b64_e32 v[100:101], 0
	v_mov_b64_e32 v[102:103], 0
	v_mov_b64_e32 v[104:105], 0
	v_mov_b64_e32 v[106:107], 0
	v_mov_b64_e32 v[108:109], 0
	v_mov_b64_e32 v[110:111], 0
	v_mov_b64_e32 v[112:113], 0
	v_mov_b64_e32 v[114:115], 0
	v_mov_b64_e32 v[116:117], 0
	v_mov_b64_e32 v[118:119], 0
	v_mov_b64_e32 v[120:121], 0
	v_mov_b64_e32 v[122:123], 0
	v_mov_b64_e32 v[124:125], 0
	v_mov_b64_e32 v[126:127], 0

;     DI size_t aoff(const Unit& u, size_t tstep) const { return (size_t)u.pm * tstep; }
;     DI size_t boff(const Unit& u, size_t tstep) const { return (size_t)u.pn * tstep; }
;     DI bool next(int i, Unit& u) const { const long L = (long)i * G + c; if (L >= np) return false; u.pm = pmv; u.pn = (int)(L % nN); u.ks = (int)(L / nN); return true; }
;     DI size_t aoff(const Unit& u, size_t) const { return (size_t)u.ks * kbytes; }
;     DI size_t boff(const Unit& u, size_t tstep) const { return (size_t)u.pn * tstep + (size_t)u.ks * kbytes; }
;     DI bool next(int i, Unit& u) const { Unit t; if (!S.next(i / 3, t)) return false; u.pm = t.pm; u.pn = t.pn; u.ks = i % 3; return true; }
;     DI size_t aoff(const Unit& u, size_t tstep) const { return (u.ks < 2 ? offU : offOA) + (size_t)u.pm * tstep; }
; template <class Epi, class Sched>
; DI void gemm_phase(LAS unsigned char* lds, const Gemm g, const Sched& S, const Epi& E) {
;     ...
;         const bool has_next = S.next(ui + 1, nxt);
;         const char* nA = has_next ? (const char*)g.A + S.aoff(nxt, tstep) : cA; const char* nB = has_next ? (const char*)g.Bt + S.boff(nxt, tstep) : cB;
;         for (int t = 0; t < nt; t += 2) {
;             if constexpr (Epi::HAS_MID) { if (t == E.mid_t(nt)) { int fr3 = fr, fq3 = fq; asm volatile("" : "+v"(fr3), "+v"(fq3)); E.mid(acc, cur, wr, wc, fr3, fq3); } }
;             const bool last = (t == nt - 2);
;             const char* a1 = cA + (size_t)(t + 1) * kstep;
;             const char* a2 = last ? nA : cA + (size_t)(t + 2) * kstep; const char* b2 = last ? nB : cB + (size_t)(t + 2) * kstep;
;             const char* a3 = a2 + kstep; const char* b3 = b2 + kstep;
;     ...
;         for (int a = 0; a < 2; ++a)
; #pragma unroll
;             for (int b = 0; b < 2; ++b)
; #pragma unroll
;                 for (int m = 0; m < 4; ++m)
; #pragma unroll
;                     for (int n = 0; n < 2; ++n) acc[a][b][m][n] = (f32x4){0.f, 0.f, 0.f, 0.f};
.LBB0_983:
	s_ashr_i32 s31, s30, 31
	s_lshl_b64 s[0:1], s[30:31], 18
	v_cmp_lt_i64_e32 vcc, s[36:37], v[142:143]
	s_add_u32 s36, s51, s0
	s_addc_u32 s37, s52, s1
	s_and_b64 s[0:1], vcc, exec
	s_cselect_b32 s9, s37, s43
	s_cselect_b32 s31, s36, s42
	s_ashr_i32 s29, s28, 31
	s_lshl_b64 s[0:1], s[28:29], 18
	s_add_u32 s38, s53, s0
	s_addc_u32 s39, s54, s1
	s_and_b64 s[0:1], vcc, exec
	s_cselect_b32 s29, s39, s45
	s_cselect_b32 s34, s38, s44
	s_add_u32 s42, s42, 0x20080
	s_addc_u32 s43, s43, 0
	s_add_u32 s35, s44, 0x100
	v_mov_b32_e32 v0, 0
	s_addc_u32 s41, s45, 0
	s_mov_b32 s79, -2
	v_mov_b32_e32 v1, 0
	v_mov_b64_e32 v[2:3], 0
	v_mov_b64_e32 v[4:5], 0
	v_mov_b64_e32 v[6:7], 0
	v_mov_b64_e32 v[8:9], 0
	v_mov_b64_e32 v[10:11], 0
	v_mov_b64_e32 v[12:13], 0
	v_mov_b64_e32 v[14:15], 0
	v_mov_b64_e32 v[16:17], 0
	v_mov_b64_e32 v[18:19], 0
	v_mov_b64_e32 v[20:21], 0
	v_mov_b64_e32 v[22:23], 0
	v_mov_b64_e32 v[24:25], 0
	v_mov_b64_e32 v[26:27], 0
	v_mov_b64_e32 v[28:29], 0
	v_mov_b64_e32 v[30:31], 0
	v_mov_b64_e32 v[32:33], 0
	v_mov_b64_e32 v[34:35], 0
	v_mov_b64_e32 v[36:37], 0
	v_mov_b64_e32 v[38:39], 0
	v_mov_b64_e32 v[40:41], 0
	v_mov_b64_e32 v[42:43], 0
	v_mov_b64_e32 v[44:45], 0
	v_mov_b64_e32 v[46:47], 0
	v_mov_b64_e32 v[48:49], 0
	v_mov_b64_e32 v[50:51], 0
	v_mov_b64_e32 v[52:53], 0
	v_mov_b64_e32 v[54:55], 0
	v_mov_b64_e32 v[56:57], 0
	v_mov_b64_e32 v[58:59], 0
	v_mov_b64_e32 v[60:61], 0
	v_mov_b64_e32 v[62:63], 0
	v_mov_b64_e32 v[64:65], 0
	v_mov_b64_e32 v[66:67], 0
	v_mov_b64_e32 v[68:69], 0
	v_mov_b64_e32 v[70:71], 0
	v_mov_b64_e32 v[72:73], 0
	v_mov_b64_e32 v[74:75], 0
	v_mov_b64_e32 v[76:77], 0
	v_mov_b64_e32 v[78:79], 0
	v_mov_b64_e32 v[80:81], 0
	v_mov_b64_e32 v[82:83], 0
	v_mov_b64_e32 v[84:85], 0
	v_mov_b64_e32 v[86:87], 0
	v_mov_b64_e32 v[88:89], 0
	v_mov_b64_e32 v[90:91], 0
	v_mov_b64_e32 v[92:93], 0
	v_mov_b64_e32 v[94:95], 0
	v_mov_b64_e32 v[96:97], 0
	v_mov_b64_e32 v[98:99], 0
	v_mov_b64_e32 v[100:101], 0
	v_mov_b64_e32 v[102:103], 0
	v_mov_b64_e32 v[104:105], 0
	v_mov_b64_e32 v[106:107], 0
	v_mov_b64_e32 v[108:109], 0
	v_mov_b64_e32 v[110:111], 0
	v_mov_b64_e32 v[112:113], 0
	v_mov_b64_e32 v[114:115], 0
	v_mov_b64_e32 v[116:117], 0
	v_mov_b64_e32 v[118:119], 0
	v_mov_b64_e32 v[120:121], 0
	v_mov_b64_e32 v[122:123], 0
	v_mov_b64_e32 v[124:125], 0
	v_mov_b64_e32 v[126:127], 0

;     DI size_t aoff(const Unit& u, size_t tstep) const { return (size_t)u.pm * tstep; }
;     DI size_t boff(const Unit& u, size_t tstep) const { return (size_t)u.pn * tstep; }
;     DI bool next(int i, Unit& u) const { Unit t; if (!S.next(i / 3, t)) return false; u.pm = t.pm; u.pn = t.pn; u.ks = i % 3; return true; }
;     DI size_t aoff(const Unit& u, size_t tstep) const { return (u.ks < 2 ? offU : offOA) + (size_t)u.pm * tstep; }
;     DI bool next(int i, Unit& u) const { const long L = (long)i * G + c; if (L >= np) return false; u.pm = pmv; u.pn = (int)(L % nN); u.ks = (int)(L / nN); return true; }
;     DI size_t aoff(const Unit& u, size_t) const { return (size_t)u.ks * kbytes; }
;     DI size_t boff(const Unit& u, size_t tstep) const { return (size_t)u.pn * tstep + (size_t)u.ks * kbytes; }
; template <class Epi, class Sched>
; DI void gemm_phase(LAS unsigned char* lds, const Gemm g, const Sched& S, const Epi& E) {
;     ...
;         for (int a = 0; a < 2; ++a)
; #pragma unroll
;             for (int b = 0; b < 2; ++b)
; #pragma unroll
;                 for (int m = 0; m < 4; ++m)
; #pragma unroll
;                     for (int n = 0; n < 2; ++n) acc[a][b][m][n] = (f32x4){0.f, 0.f, 0.f, 0.f};
.LBB0_1364:
	s_ashr_i32 s37, s36, 31
	s_lshl_b64 s[4:5], s[36:37], 9
	v_cmp_lt_i64_e64 s[0:1], s[42:43], 64
	s_add_u32 s42, s62, s4
	s_addc_u32 s43, s63, s5
	s_and_b64 s[44:45], s[0:1], exec
	s_cselect_b32 s19, s43, s31
	s_cselect_b32 s37, s42, s30
	s_ashr_i32 s39, s38, 31
	s_lshl_b64 s[44:45], s[38:39], 20
	s_add_u32 s33, s64, s44
	s_addc_u32 s39, s65, s45
	s_add_u32 s4, s33, s4
	s_addc_u32 s5, s39, s5
	s_and_b64 s[0:1], s[0:1], exec
	v_mov_b32_e32 v0, 0
	s_cselect_b32 s45, s5, s29
	s_cselect_b32 s44, s4, s28
	s_mov_b32 s0, 0
	s_mov_b64 s[46:47], -1
	s_mov_b64 s[48:49], 0
	v_mov_b32_e32 v1, 0
	v_mov_b64_e32 v[2:3], 0
	v_mov_b64_e32 v[4:5], 0
	v_mov_b64_e32 v[6:7], 0
	v_mov_b64_e32 v[8:9], 0
	v_mov_b64_e32 v[10:11], 0
	v_mov_b64_e32 v[12:13], 0
	v_mov_b64_e32 v[14:15], 0
	v_mov_b64_e32 v[16:17], 0
	v_mov_b64_e32 v[18:19], 0
	v_mov_b64_e32 v[20:21], 0
	v_mov_b64_e32 v[22:23], 0
	v_mov_b64_e32 v[24:25], 0
	v_mov_b64_e32 v[26:27], 0
	v_mov_b64_e32 v[28:29], 0
	v_mov_b64_e32 v[30:31], 0
	v_mov_b64_e32 v[32:33], 0
	v_mov_b64_e32 v[34:35], 0
	v_mov_b64_e32 v[36:37], 0
	v_mov_b64_e32 v[38:39], 0
	v_mov_b64_e32 v[40:41], 0
	v_mov_b64_e32 v[42:43], 0
	v_mov_b64_e32 v[44:45], 0
	v_mov_b64_e32 v[46:47], 0
	v_mov_b64_e32 v[48:49], 0
	v_mov_b64_e32 v[50:51], 0
	v_mov_b64_e32 v[52:53], 0
	v_mov_b64_e32 v[54:55], 0
	v_mov_b64_e32 v[56:57], 0
	v_mov_b64_e32 v[58:59], 0
	v_mov_b64_e32 v[60:61], 0
	v_mov_b64_e32 v[62:63], 0
	v_mov_b64_e32 v[64:65], 0
	v_mov_b64_e32 v[66:67], 0
	v_mov_b64_e32 v[68:69], 0
	v_mov_b64_e32 v[70:71], 0
	v_mov_b64_e32 v[72:73], 0
	v_mov_b64_e32 v[74:75], 0
	v_mov_b64_e32 v[76:77], 0
	v_mov_b64_e32 v[78:79], 0
	v_mov_b64_e32 v[80:81], 0
	v_mov_b64_e32 v[82:83], 0
	v_mov_b64_e32 v[84:85], 0
	v_mov_b64_e32 v[86:87], 0
	v_mov_b64_e32 v[88:89], 0
	v_mov_b64_e32 v[90:91], 0
	v_mov_b64_e32 v[92:93], 0
	v_mov_b64_e32 v[94:95], 0
	v_mov_b64_e32 v[96:97], 0
	v_mov_b64_e32 v[98:99], 0
	v_mov_b64_e32 v[100:101], 0
	v_mov_b64_e32 v[102:103], 0
	v_mov_b64_e32 v[104:105], 0
	v_mov_b64_e32 v[106:107], 0
	v_mov_b64_e32 v[108:109], 0
	v_mov_b64_e32 v[110:111], 0
	v_mov_b64_e32 v[112:113], 0
	v_mov_b64_e32 v[114:115], 0
	v_mov_b64_e32 v[116:117], 0
	v_mov_b64_e32 v[118:119], 0
	v_mov_b64_e32 v[120:121], 0
	v_mov_b64_e32 v[122:123], 0
	v_mov_b64_e32 v[124:125], 0
	v_mov_b64_e32 v[126:127], 0

;     DI size_t aoff(const Unit& u, size_t tstep) const { return (size_t)u.pm * tstep; }
;     DI size_t boff(const Unit& u, size_t tstep) const { return (size_t)u.pn * tstep; }
;     DI bool next(int i, Unit& u) const { Unit t; if (!S.next(i / 3, t)) return false; u.pm = t.pm; u.pn = t.pn; u.ks = i % 3; return true; }
;     DI size_t aoff(const Unit& u, size_t tstep) const { return (u.ks < 2 ? offU : offOA) + (size_t)u.pm * tstep; }
;     DI bool next(int i, Unit& u) const { const long L = (long)i * G + c; if (L >= np) return false; u.pm = pmv; u.pn = (int)(L % nN); u.ks = (int)(L / nN); return true; }
;     DI size_t aoff(const Unit& u, size_t) const { return (size_t)u.ks * kbytes; }
;     DI size_t boff(const Unit& u, size_t tstep) const { return (size_t)u.pn * tstep + (size_t)u.ks * kbytes; }
; template <class Epi, class Sched>
; DI void gemm_phase(LAS unsigned char* lds, const Gemm g, const Sched& S, const Epi& E) {
;     ...
;         for (int a = 0; a < 2; ++a)
; #pragma unroll
;             for (int b = 0; b < 2; ++b)
; #pragma unroll
;                 for (int m = 0; m < 4; ++m)
; #pragma unroll
;                     for (int n = 0; n < 2; ++n) acc[a][b][m][n] = (f32x4){0.f, 0.f, 0.f, 0.f};
.LBB0_1376:
	s_ashr_i32 s41, s40, 31
	s_lshl_b64 s[0:1], s[40:41], 9
	v_cmp_lt_i64_e32 vcc, s[44:45], v[128:129]
	s_add_u32 s44, s63, s0
	s_addc_u32 s45, s64, s1
	s_and_b64 s[4:5], vcc, exec
	s_cselect_b32 s31, s45, s39
	s_cselect_b32 s41, s44, s38
	s_ashr_i32 s43, s42, 31
	s_lshl_b64 s[4:5], s[42:43], 20
	s_add_u32 s4, s65, s4
	s_addc_u32 s5, s66, s5
	s_add_u32 s4, s4, s0
	s_addc_u32 s5, s5, s1
	s_and_b64 s[0:1], vcc, exec
	v_mov_b32_e32 v0, 0
	s_cselect_b32 s47, s5, s37
	s_cselect_b32 s46, s4, s36
	s_mov_b32 s0, 0
	s_mov_b64 s[48:49], -1
	s_mov_b64 s[50:51], 0
	v_mov_b32_e32 v1, 0
	v_mov_b64_e32 v[2:3], 0
	v_mov_b64_e32 v[4:5], 0
	v_mov_b64_e32 v[6:7], 0
	v_mov_b64_e32 v[8:9], 0
	v_mov_b64_e32 v[10:11], 0
	v_mov_b64_e32 v[12:13], 0
	v_mov_b64_e32 v[14:15], 0
	v_mov_b64_e32 v[16:17], 0
	v_mov_b64_e32 v[18:19], 0
	v_mov_b64_e32 v[20:21], 0
	v_mov_b64_e32 v[22:23], 0
	v_mov_b64_e32 v[24:25], 0
	v_mov_b64_e32 v[26:27], 0
	v_mov_b64_e32 v[28:29], 0
	v_mov_b64_e32 v[30:31], 0
	v_mov_b64_e32 v[32:33], 0
	v_mov_b64_e32 v[34:35], 0
	v_mov_b64_e32 v[36:37], 0
	v_mov_b64_e32 v[38:39], 0
	v_mov_b64_e32 v[40:41], 0
	v_mov_b64_e32 v[42:43], 0
	v_mov_b64_e32 v[44:45], 0
	v_mov_b64_e32 v[46:47], 0
	v_mov_b64_e32 v[48:49], 0
	v_mov_b64_e32 v[50:51], 0
	v_mov_b64_e32 v[52:53], 0
	v_mov_b64_e32 v[54:55], 0
	v_mov_b64_e32 v[56:57], 0
	v_mov_b64_e32 v[58:59], 0
	v_mov_b64_e32 v[60:61], 0
	v_mov_b64_e32 v[62:63], 0
	v_mov_b64_e32 v[64:65], 0
	v_mov_b64_e32 v[66:67], 0
	v_mov_b64_e32 v[68:69], 0
	v_mov_b64_e32 v[70:71], 0
	v_mov_b64_e32 v[72:73], 0
	v_mov_b64_e32 v[74:75], 0
	v_mov_b64_e32 v[76:77], 0
	v_mov_b64_e32 v[78:79], 0
	v_mov_b64_e32 v[80:81], 0
	v_mov_b64_e32 v[82:83], 0
	v_mov_b64_e32 v[84:85], 0
	v_mov_b64_e32 v[86:87], 0
	v_mov_b64_e32 v[88:89], 0
	v_mov_b64_e32 v[90:91], 0
	v_mov_b64_e32 v[92:93], 0
	v_mov_b64_e32 v[94:95], 0
	v_mov_b64_e32 v[96:97], 0
	v_mov_b64_e32 v[98:99], 0
	v_mov_b64_e32 v[100:101], 0
	v_mov_b64_e32 v[102:103], 0
	v_mov_b64_e32 v[104:105], 0
	v_mov_b64_e32 v[106:107], 0
	v_mov_b64_e32 v[108:109], 0
	v_mov_b64_e32 v[110:111], 0
	v_mov_b64_e32 v[112:113], 0
	v_mov_b64_e32 v[114:115], 0
	v_mov_b64_e32 v[116:117], 0
	v_mov_b64_e32 v[118:119], 0
	v_mov_b64_e32 v[120:121], 0
	v_mov_b64_e32 v[122:123], 0
	v_mov_b64_e32 v[124:125], 0
	v_mov_b64_e32 v[126:127], 0

;     DI size_t aoff(const Unit& u, size_t tstep) const { return (size_t)u.pm * tstep; }
;     DI size_t boff(const Unit& u, size_t tstep) const { return (size_t)u.pn * tstep; }
;     DI bool next(int i, Unit& u) const { const long L = (long)i * G + c; if (L >= np) return false; u.pm = pmv; u.pn = (int)(L % nN); u.ks = (int)(L / nN); return true; }
;     DI size_t aoff(const Unit& u, size_t) const { return (size_t)u.ks * kbytes; }
;     DI size_t boff(const Unit& u, size_t tstep) const { return (size_t)u.pn * tstep + (size_t)u.ks * kbytes; }
;     DI bool next(int i, Unit& u) const { Unit t; if (!S.next(i / 3, t)) return false; u.pm = t.pm; u.pn = t.pn; u.ks = i % 3; return true; }
;     DI size_t aoff(const Unit& u, size_t tstep) const { return (u.ks < 2 ? offU : offOA) + (size_t)u.pm * tstep; }
; template <class Epi, class Sched>
; DI void gemm_phase(LAS unsigned char* lds, const Gemm g, const Sched& S, const Epi& E) {
;     ...
;         const bool has_next = S.next(ui + 1, nxt);
;         const char* nA = has_next ? (const char*)g.A + S.aoff(nxt, tstep) : cA; const char* nB = has_next ? (const char*)g.Bt + S.boff(nxt, tstep) : cB;
;         for (int t = 0; t < nt; t += 2) {
;             if constexpr (Epi::HAS_MID) { if (t == E.mid_t(nt)) { int fr3 = fr, fq3 = fq; asm volatile("" : "+v"(fr3), "+v"(fq3)); E.mid(acc, cur, wr, wc, fr3, fq3); } }
;             const bool last = (t == nt - 2);
;             const char* a1 = cA + (size_t)(t + 1) * kstep;
;             const char* a2 = last ? nA : cA + (size_t)(t + 2) * kstep; const char* b2 = last ? nB : cB + (size_t)(t + 2) * kstep;
;             const char* a3 = a2 + kstep; const char* b3 = b2 + kstep;
;     ...
;         for (int a = 0; a < 2; ++a)
; #pragma unroll
;             for (int b = 0; b < 2; ++b)
; #pragma unroll
;                 for (int m = 0; m < 4; ++m)
; #pragma unroll
;                     for (int n = 0; n < 2; ++n) acc[a][b][m][n] = (f32x4){0.f, 0.f, 0.f, 0.f};
.LBB0_1507:
	s_ashr_i32 s37, s36, 31
	s_lshl_b64 s[0:1], s[36:37], 20
	v_cmp_lt_i64_e32 vcc, s[38:39], v[140:141]
	s_add_u32 s38, s13, s0
	s_addc_u32 s39, s50, s1
	s_and_b64 s[0:1], vcc, exec
	s_cselect_b32 s34, s39, s45
	s_cselect_b32 s35, s38, s44
	s_ashr_i32 s31, s30, 31
	s_lshl_b64 s[0:1], s[30:31], 20
	s_add_u32 s40, s55, s0
	s_addc_u32 s41, s56, s1
	s_and_b64 s[0:1], vcc, exec
	s_cselect_b32 s31, s41, s47
	s_cselect_b32 s37, s40, s46
	s_add_u32 s44, s44, 0x80080
	s_addc_u32 s45, s45, 0
	s_add_u32 s43, s46, 0x100
	v_mov_b32_e32 v0, 0
	s_addc_u32 s68, s47, 0
	s_mov_b32 s69, -2
	s_waitcnt lgkmcnt(0)
	v_mov_b32_e32 v1, 0
	v_mov_b64_e32 v[2:3], 0
	v_mov_b64_e32 v[4:5], 0
	v_mov_b64_e32 v[6:7], 0
	v_mov_b64_e32 v[8:9], 0
	v_mov_b64_e32 v[10:11], 0
	v_mov_b64_e32 v[12:13], 0
	v_mov_b64_e32 v[14:15], 0
	v_mov_b64_e32 v[16:17], 0
	v_mov_b64_e32 v[18:19], 0
	v_mov_b64_e32 v[20:21], 0
	v_mov_b64_e32 v[22:23], 0
	v_mov_b64_e32 v[24:25], 0
	v_mov_b64_e32 v[26:27], 0
	v_mov_b64_e32 v[28:29], 0
	v_mov_b64_e32 v[30:31], 0
	v_mov_b64_e32 v[32:33], 0
	v_mov_b64_e32 v[34:35], 0
	v_mov_b64_e32 v[36:37], 0
	v_mov_b64_e32 v[38:39], 0
	v_mov_b64_e32 v[40:41], 0
	v_mov_b64_e32 v[42:43], 0
	v_mov_b64_e32 v[44:45], 0
	v_mov_b64_e32 v[46:47], 0
	v_mov_b64_e32 v[48:49], 0
	v_mov_b64_e32 v[50:51], 0
	v_mov_b64_e32 v[52:53], 0
	v_mov_b64_e32 v[54:55], 0
	v_mov_b64_e32 v[56:57], 0
	v_mov_b64_e32 v[58:59], 0
	v_mov_b64_e32 v[60:61], 0
	v_mov_b64_e32 v[62:63], 0
	v_mov_b64_e32 v[64:65], 0
	v_mov_b64_e32 v[66:67], 0
	v_mov_b64_e32 v[68:69], 0
	v_mov_b64_e32 v[70:71], 0
	v_mov_b64_e32 v[72:73], 0
	v_mov_b64_e32 v[74:75], 0
	v_mov_b64_e32 v[76:77], 0
	v_mov_b64_e32 v[78:79], 0
	v_mov_b64_e32 v[80:81], 0
	v_mov_b64_e32 v[82:83], 0
	v_mov_b64_e32 v[84:85], 0
	v_mov_b64_e32 v[86:87], 0
	v_mov_b64_e32 v[88:89], 0
	v_mov_b64_e32 v[90:91], 0
	v_mov_b64_e32 v[92:93], 0
	v_mov_b64_e32 v[94:95], 0
	v_mov_b64_e32 v[96:97], 0
	v_mov_b64_e32 v[98:99], 0
	v_mov_b64_e32 v[100:101], 0
	v_mov_b64_e32 v[102:103], 0
	v_mov_b64_e32 v[104:105], 0
	v_mov_b64_e32 v[106:107], 0
	v_mov_b64_e32 v[108:109], 0
	v_mov_b64_e32 v[110:111], 0
	v_mov_b64_e32 v[112:113], 0
	v_mov_b64_e32 v[114:115], 0
	v_mov_b64_e32 v[116:117], 0
	v_mov_b64_e32 v[118:119], 0
	v_mov_b64_e32 v[120:121], 0
	v_mov_b64_e32 v[122:123], 0
	v_mov_b64_e32 v[124:125], 0
	v_mov_b64_e32 v[126:127], 0

;     DI size_t aoff(const Unit& u, size_t tstep) const { return (size_t)u.pm * tstep; }
;     DI size_t boff(const Unit& u, size_t tstep) const { return (size_t)u.pn * tstep; }
;     DI bool next(int i, Unit& u) const { Unit t; if (!S.next(i / 3, t)) return false; u.pm = t.pm; u.pn = t.pn; u.ks = i % 3; return true; }
;     DI size_t aoff(const Unit& u, size_t tstep) const { return (u.ks < 2 ? offU : offOA) + (size_t)u.pm * tstep; }
;     DI bool next(int i, Unit& u) const { const long L = (long)i * G + c; if (L >= np) return false; u.pm = pmv; u.pn = (int)(L % nN); u.ks = (int)(L / nN); return true; }
;     DI size_t aoff(const Unit& u, size_t) const { return (size_t)u.ks * kbytes; }
;     DI size_t boff(const Unit& u, size_t tstep) const { return (size_t)u.pn * tstep + (size_t)u.ks * kbytes; }
; template <class Epi, class Sched>
; DI void gemm_phase(LAS unsigned char* lds, const Gemm g, const Sched& S, const Epi& E) {
;     ...
;         for (int a = 0; a < 2; ++a)
; #pragma unroll
;             for (int b = 0; b < 2; ++b)
; #pragma unroll
;                 for (int m = 0; m < 4; ++m)
; #pragma unroll
;                     for (int n = 0; n < 2; ++n) acc[a][b][m][n] = (f32x4){0.f, 0.f, 0.f, 0.f};
.LBB0_1534:
	s_ashr_i32 s19, s18, 31
	s_lshl_b64 s[4:5], s[18:19], 9
	v_cmp_lt_i64_e64 s[0:1], s[36:37], 64
	s_add_u32 s36, s58, s4
	s_addc_u32 s37, s59, s5
	s_and_b64 s[38:39], s[0:1], exec
	s_cselect_b32 s13, s37, s17
	s_cselect_b32 s19, s36, s16
	s_ashr_i32 s29, s28, 31
	s_lshl_b64 s[38:39], s[28:29], 20
	s_add_u32 s29, s55, s38
	s_addc_u32 s33, s56, s39
	s_add_u32 s4, s29, s4
	s_addc_u32 s5, s33, s5
	s_and_b64 s[0:1], s[0:1], exec
	v_mov_b32_e32 v0, 0
	s_cselect_b32 s39, s5, s15
	s_cselect_b32 s38, s4, s14
	s_mov_b32 s0, 0
	s_mov_b64 s[40:41], -1
	s_mov_b64 s[42:43], 0
	v_mov_b32_e32 v1, 0
	v_mov_b64_e32 v[2:3], 0
	v_mov_b64_e32 v[4:5], 0
	v_mov_b64_e32 v[6:7], 0
	v_mov_b64_e32 v[8:9], 0
	v_mov_b64_e32 v[10:11], 0
	v_mov_b64_e32 v[12:13], 0
	v_mov_b64_e32 v[14:15], 0
	v_mov_b64_e32 v[16:17], 0
	v_mov_b64_e32 v[18:19], 0
	v_mov_b64_e32 v[20:21], 0
	v_mov_b64_e32 v[22:23], 0
	v_mov_b64_e32 v[24:25], 0
	v_mov_b64_e32 v[26:27], 0
	v_mov_b64_e32 v[28:29], 0
	v_mov_b64_e32 v[30:31], 0
	v_mov_b64_e32 v[32:33], 0
	v_mov_b64_e32 v[34:35], 0
	v_mov_b64_e32 v[36:37], 0
	v_mov_b64_e32 v[38:39], 0
	v_mov_b64_e32 v[40:41], 0
	v_mov_b64_e32 v[42:43], 0
	v_mov_b64_e32 v[44:45], 0
	v_mov_b64_e32 v[46:47], 0
	v_mov_b64_e32 v[48:49], 0
	v_mov_b64_e32 v[50:51], 0
	v_mov_b64_e32 v[52:53], 0
	v_mov_b64_e32 v[54:55], 0
	v_mov_b64_e32 v[56:57], 0
	v_mov_b64_e32 v[58:59], 0
	v_mov_b64_e32 v[60:61], 0
	v_mov_b64_e32 v[62:63], 0
	v_mov_b64_e32 v[64:65], 0
	v_mov_b64_e32 v[66:67], 0
	v_mov_b64_e32 v[68:69], 0
	v_mov_b64_e32 v[70:71], 0
	v_mov_b64_e32 v[72:73], 0
	v_mov_b64_e32 v[74:75], 0
	v_mov_b64_e32 v[76:77], 0
	v_mov_b64_e32 v[78:79], 0
	v_mov_b64_e32 v[80:81], 0
	v_mov_b64_e32 v[82:83], 0
	v_mov_b64_e32 v[84:85], 0
	v_mov_b64_e32 v[86:87], 0
	v_mov_b64_e32 v[88:89], 0
	v_mov_b64_e32 v[90:91], 0
	v_mov_b64_e32 v[92:93], 0
	v_mov_b64_e32 v[94:95], 0
	v_mov_b64_e32 v[96:97], 0
	v_mov_b64_e32 v[98:99], 0
	v_mov_b64_e32 v[100:101], 0
	v_mov_b64_e32 v[102:103], 0
	v_mov_b64_e32 v[104:105], 0
	v_mov_b64_e32 v[106:107], 0
	v_mov_b64_e32 v[108:109], 0
	v_mov_b64_e32 v[110:111], 0
	v_mov_b64_e32 v[112:113], 0
	v_mov_b64_e32 v[114:115], 0
	v_mov_b64_e32 v[116:117], 0
	v_mov_b64_e32 v[118:119], 0
	v_mov_b64_e32 v[120:121], 0
	v_mov_b64_e32 v[122:123], 0
	v_mov_b64_e32 v[124:125], 0
	v_mov_b64_e32 v[126:127], 0

;     DI size_t aoff(const Unit& u, size_t tstep) const { return (size_t)u.pm * tstep; }
;     DI size_t boff(const Unit& u, size_t tstep) const { return (size_t)u.pn * tstep; }
;     DI bool next(int i, Unit& u) const { const long L = (long)i * G + c; if (L >= np) return false; u.pm = pmv; u.pn = (int)(L % nN); u.ks = (int)(L / nN); return true; }
;     DI size_t aoff(const Unit& u, size_t) const { return (size_t)u.ks * kbytes; }
;     DI size_t boff(const Unit& u, size_t tstep) const { return (size_t)u.pn * tstep + (size_t)u.ks * kbytes; }
;     DI bool next(int i, Unit& u) const { Unit t; if (!S.next(i / 3, t)) return false; u.pm = t.pm; u.pn = t.pn; u.ks = i % 3; return true; }
;     DI size_t aoff(const Unit& u, size_t tstep) const { return (u.ks < 2 ? offU : offOA) + (size_t)u.pm * tstep; }
; template <class Epi, class Sched>
; DI void gemm_phase(LAS unsigned char* lds, const Gemm g, const Sched& S, const Epi& E) {
;     ...
;         const bool has_next = S.next(ui + 1, nxt);
;         const char* nA = has_next ? (const char*)g.A + S.aoff(nxt, tstep) : cA; const char* nB = has_next ? (const char*)g.Bt + S.boff(nxt, tstep) : cB;
;         for (int t = 0; t < nt; t += 2) {
;             if constexpr (Epi::HAS_MID) { if (t == E.mid_t(nt)) { int fr3 = fr, fq3 = fq; asm volatile("" : "+v"(fr3), "+v"(fq3)); E.mid(acc, cur, wr, wc, fr3, fq3); } }
;             const bool last = (t == nt - 2);
;             const char* a1 = cA + (size_t)(t + 1) * kstep;
;             const char* a2 = last ? nA : cA + (size_t)(t + 2) * kstep; const char* b2 = last ? nB : cB + (size_t)(t + 2) * kstep;
;             const char* a3 = a2 + kstep; const char* b3 = b2 + kstep;
;     ...
;         for (int a = 0; a < 2; ++a)
; #pragma unroll
;             for (int b = 0; b < 2; ++b)
; #pragma unroll
;                 for (int m = 0; m < 4; ++m)
; #pragma unroll
;                     for (int n = 0; n < 2; ++n) acc[a][b][m][n] = (f32x4){0.f, 0.f, 0.f, 0.f};
.LBB0_1667:
	s_ashr_i32 s29, s28, 31
	s_lshl_b64 s[0:1], s[28:29], 20
	s_add_u32 s30, s45, s0
	v_cmp_lt_i64_e32 vcc, s[8:9], v[140:141]
	s_addc_u32 s31, s46, s1
	s_and_b64 s[0:1], vcc, exec
	s_cselect_b32 s29, s31, s43
	s_cselect_b32 s35, s30, s42
	s_ashr_i32 s19, s18, 31
	s_lshl_b64 s[0:1], s[18:19], 20
	s_add_u32 s36, s47, s0
	s_addc_u32 s37, s48, s1
	s_and_b64 s[0:1], vcc, exec
	s_cselect_b32 s19, s37, s41
	s_cselect_b32 s65, s36, s40
	s_add_u32 s8, s42, 0x80080
	s_addc_u32 s9, s43, 0
	s_add_u32 s66, s40, 0x100
	v_mov_b32_e32 v8, 0
	s_addc_u32 s67, s41, 0
	s_mov_b32 s68, -2
	v_mov_b64_e32 v[0:1], 0
	v_mov_b64_e32 v[2:3], 0
	v_mov_b64_e32 v[4:5], 0
	v_mov_b64_e32 v[6:7], 0
	v_mov_b32_e32 v9, 0
	v_mov_b64_e32 v[10:11], 0
	v_mov_b64_e32 v[12:13], 0
	v_mov_b64_e32 v[14:15], 0
	v_mov_b64_e32 v[16:17], 0
	v_mov_b64_e32 v[18:19], 0
	v_mov_b64_e32 v[20:21], 0
	v_mov_b64_e32 v[22:23], 0
	v_mov_b64_e32 v[24:25], 0
	v_mov_b64_e32 v[26:27], 0
	v_mov_b64_e32 v[28:29], 0
	v_mov_b64_e32 v[30:31], 0
	v_mov_b64_e32 v[32:33], 0
	v_mov_b64_e32 v[34:35], 0
	v_mov_b64_e32 v[36:37], 0
	v_mov_b64_e32 v[38:39], 0
	v_mov_b64_e32 v[40:41], 0
	v_mov_b64_e32 v[42:43], 0
	v_mov_b64_e32 v[44:45], 0
	v_mov_b64_e32 v[46:47], 0
	v_mov_b64_e32 v[48:49], 0
	v_mov_b64_e32 v[50:51], 0
	v_mov_b64_e32 v[52:53], 0
	v_mov_b64_e32 v[54:55], 0
	v_mov_b64_e32 v[56:57], 0
	v_mov_b64_e32 v[58:59], 0
	v_mov_b64_e32 v[60:61], 0
	v_mov_b64_e32 v[62:63], 0
	v_mov_b64_e32 v[64:65], 0
	v_mov_b64_e32 v[66:67], 0
	v_mov_b64_e32 v[68:69], 0
	v_mov_b64_e32 v[70:71], 0
	v_mov_b64_e32 v[72:73], 0
	v_mov_b64_e32 v[74:75], 0
	v_mov_b64_e32 v[76:77], 0
	v_mov_b64_e32 v[78:79], 0
	v_mov_b64_e32 v[80:81], 0
	v_mov_b64_e32 v[82:83], 0
	v_mov_b64_e32 v[84:85], 0
	v_mov_b64_e32 v[86:87], 0
	v_mov_b64_e32 v[88:89], 0
	v_mov_b64_e32 v[90:91], 0
	v_mov_b64_e32 v[92:93], 0
	v_mov_b64_e32 v[94:95], 0
	v_mov_b64_e32 v[96:97], 0
	v_mov_b64_e32 v[98:99], 0
	v_mov_b64_e32 v[100:101], 0
	v_mov_b64_e32 v[102:103], 0
	v_mov_b64_e32 v[104:105], 0
	v_mov_b64_e32 v[106:107], 0
	v_mov_b64_e32 v[108:109], 0
	v_mov_b64_e32 v[110:111], 0
	v_mov_b64_e32 v[112:113], 0
	v_mov_b64_e32 v[114:115], 0
	v_mov_b64_e32 v[116:117], 0
	v_mov_b64_e32 v[118:119], 0
	v_mov_b64_e32 v[120:121], 0
	v_mov_b64_e32 v[122:123], 0
	v_mov_b64_e32 v[124:125], 0
	v_mov_b64_e32 v[126:127], 0

;     DI size_t aoff(const Unit& u, size_t tstep) const { return (size_t)u.pm * tstep; }
;     DI size_t boff(const Unit& u, size_t tstep) const { return (size_t)u.pn * tstep; }
;     DI bool next(int i, Unit& u) const { const long L = (long)i * G + c; if (L >= np) return false; u.pm = pmv; u.pn = (int)(L % nN); u.ks = (int)(L / nN); return true; }
;     DI size_t aoff(const Unit& u, size_t) const { return (size_t)u.ks * kbytes; }
;     DI size_t boff(const Unit& u, size_t tstep) const { return (size_t)u.pn * tstep + (size_t)u.ks * kbytes; }
;     DI bool next(int i, Unit& u) const { Unit t; if (!S.next(i / 3, t)) return false; u.pm = t.pm; u.pn = t.pn; u.ks = i % 3; return true; }
;     DI size_t aoff(const Unit& u, size_t tstep) const { return (u.ks < 2 ? offU : offOA) + (size_t)u.pm * tstep; }
; template <class Epi, class Sched>
; DI void gemm_phase(LAS unsigned char* lds, const Gemm g, const Sched& S, const Epi& E) {
;     ...
;         const bool has_next = S.next(ui + 1, nxt);
;         const char* nA = has_next ? (const char*)g.A + S.aoff(nxt, tstep) : cA; const char* nB = has_next ? (const char*)g.Bt + S.boff(nxt, tstep) : cB;
;         for (int t = 0; t < nt; t += 2) {
;             if constexpr (Epi::HAS_MID) { if (t == E.mid_t(nt)) { int fr3 = fr, fq3 = fq; asm volatile("" : "+v"(fr3), "+v"(fq3)); E.mid(acc, cur, wr, wc, fr3, fq3); } }
;             const bool last = (t == nt - 2);
;             const char* a1 = cA + (size_t)(t + 1) * kstep;
;             const char* a2 = last ? nA : cA + (size_t)(t + 2) * kstep; const char* b2 = last ? nB : cB + (size_t)(t + 2) * kstep;
;             const char* a3 = a2 + kstep; const char* b3 = b2 + kstep;
;     ...
;         for (int a = 0; a < 2; ++a)
; #pragma unroll
;             for (int b = 0; b < 2; ++b)
; #pragma unroll
;                 for (int m = 0; m < 4; ++m)
; #pragma unroll
;                     for (int n = 0; n < 2; ++n) acc[a][b][m][n] = (f32x4){0.f, 0.f, 0.f, 0.f};
.LBB0_1745:
	s_add_u32 s38, s38, 0x160080
	s_addc_u32 s39, s39, 0
	s_add_u32 s35, s40, 0x100
	v_mov_b32_e32 v0, 0
	s_addc_u32 s67, s41, 0
	s_mov_b32 s68, -2
	s_waitcnt lgkmcnt(0)
	v_mov_b32_e32 v1, 0
	v_mov_b64_e32 v[2:3], 0
	v_mov_b64_e32 v[4:5], 0
	v_mov_b64_e32 v[6:7], 0
	v_mov_b64_e32 v[8:9], 0
	v_mov_b64_e32 v[10:11], 0
	v_mov_b64_e32 v[12:13], 0
	v_mov_b64_e32 v[14:15], 0
	v_mov_b64_e32 v[16:17], 0
	v_mov_b64_e32 v[18:19], 0
	v_mov_b64_e32 v[20:21], 0
	v_mov_b64_e32 v[22:23], 0
	v_mov_b64_e32 v[24:25], 0
	v_mov_b64_e32 v[26:27], 0
	v_mov_b64_e32 v[28:29], 0
	v_mov_b64_e32 v[30:31], 0
	v_mov_b64_e32 v[32:33], 0
	v_mov_b64_e32 v[34:35], 0
	v_mov_b64_e32 v[36:37], 0
	v_mov_b64_e32 v[38:39], 0
	v_mov_b64_e32 v[40:41], 0
	v_mov_b64_e32 v[42:43], 0
	v_mov_b64_e32 v[44:45], 0
	v_mov_b64_e32 v[46:47], 0
	v_mov_b64_e32 v[48:49], 0
	v_mov_b64_e32 v[50:51], 0
	v_mov_b64_e32 v[52:53], 0
	v_mov_b64_e32 v[54:55], 0
	v_mov_b64_e32 v[56:57], 0
	v_mov_b64_e32 v[58:59], 0
	v_mov_b64_e32 v[60:61], 0
	v_mov_b64_e32 v[62:63], 0
	v_mov_b64_e32 v[64:65], 0
	v_mov_b64_e32 v[66:67], 0
	v_mov_b64_e32 v[68:69], 0
	v_mov_b64_e32 v[70:71], 0
	v_mov_b64_e32 v[72:73], 0
	v_mov_b64_e32 v[74:75], 0
	v_mov_b64_e32 v[76:77], 0
	v_mov_b64_e32 v[78:79], 0
	v_mov_b64_e32 v[80:81], 0
	v_mov_b64_e32 v[82:83], 0
	v_mov_b64_e32 v[84:85], 0
	v_mov_b64_e32 v[86:87], 0
	v_mov_b64_e32 v[88:89], 0
	v_mov_b64_e32 v[90:91], 0
	v_mov_b64_e32 v[92:93], 0
	v_mov_b64_e32 v[94:95], 0
	v_mov_b64_e32 v[96:97], 0
	v_mov_b64_e32 v[98:99], 0
	v_mov_b64_e32 v[100:101], 0
	v_mov_b64_e32 v[102:103], 0
	v_mov_b64_e32 v[104:105], 0
	v_mov_b64_e32 v[106:107], 0
	v_mov_b64_e32 v[108:109], 0
	v_mov_b64_e32 v[110:111], 0
	v_mov_b64_e32 v[112:113], 0
	v_mov_b64_e32 v[114:115], 0
	v_mov_b64_e32 v[116:117], 0
	v_mov_b64_e32 v[118:119], 0
	v_mov_b64_e32 v[120:121], 0
	v_mov_b64_e32 v[122:123], 0
	v_mov_b64_e32 v[124:125], 0
	v_mov_b64_e32 v[126:127], 0

;     DI size_t aoff(const Unit& u, size_t tstep) const { return (size_t)u.pm * tstep; }
;     DI size_t boff(const Unit& u, size_t tstep) const { return (size_t)u.pn * tstep; }
;     DI bool next(int i, Unit& u) const { const long L = (long)i * G + c; if (L >= np) return false; u.pm = pmv; u.pn = (int)(L % nN); u.ks = (int)(L / nN); return true; }
;     DI size_t aoff(const Unit& u, size_t) const { return (size_t)u.ks * kbytes; }
;     DI size_t boff(const Unit& u, size_t tstep) const { return (size_t)u.pn * tstep + (size_t)u.ks * kbytes; }
;     DI bool next(int i, Unit& u) const { Unit t; if (!S.next(i / 3, t)) return false; u.pm = t.pm; u.pn = t.pn; u.ks = i % 3; return true; }
;     DI size_t aoff(const Unit& u, size_t tstep) const { return (u.ks < 2 ? offU : offOA) + (size_t)u.pm * tstep; }
; template <class Epi, class Sched>
; DI void gemm_phase(LAS unsigned char* lds, const Gemm g, const Sched& S, const Epi& E) {
;     ...
;         const bool has_next = S.next(ui + 1, nxt);
;         const char* nA = has_next ? (const char*)g.A + S.aoff(nxt, tstep) : cA; const char* nB = has_next ? (const char*)g.Bt + S.boff(nxt, tstep) : cB;
;         for (int t = 0; t < nt; t += 2) {
;             if constexpr (Epi::HAS_MID) { if (t == E.mid_t(nt)) { int fr3 = fr, fq3 = fq; asm volatile("" : "+v"(fr3), "+v"(fq3)); E.mid(acc, cur, wr, wc, fr3, fq3); } }
;             const bool last = (t == nt - 2);
;             const char* a1 = cA + (size_t)(t + 1) * kstep;
;             const char* a2 = last ? nA : cA + (size_t)(t + 2) * kstep; const char* b2 = last ? nB : cB + (size_t)(t + 2) * kstep;
;             const char* a3 = a2 + kstep; const char* b3 = b2 + kstep;
;     ...
;         for (int a = 0; a < 2; ++a)
; #pragma unroll
;             for (int b = 0; b < 2; ++b)
; #pragma unroll
;                 for (int m = 0; m < 4; ++m)
; #pragma unroll
;                     for (int n = 0; n < 2; ++n) acc[a][b][m][n] = (f32x4){0.f, 0.f, 0.f, 0.f};
.LBB0_1774:
	s_add_u32 s28, s38, s28
	s_addc_u32 s29, s39, s29
	s_and_b64 s[0:1], s[8:9], exec
	s_cselect_b32 s15, s29, s37
	s_cselect_b32 s17, s28, s36
	s_add_u32 s8, s36, 0x160080
	s_addc_u32 s9, s37, 0
	s_add_u32 s64, s30, 0x100
	v_mov_b32_e32 v0, 0
	s_addc_u32 s65, s31, 0
	s_mov_b32 s66, -2
	v_mov_b32_e32 v1, 0
	v_mov_b64_e32 v[2:3], 0
	v_mov_b64_e32 v[4:5], 0
	v_mov_b64_e32 v[6:7], 0
	v_mov_b64_e32 v[8:9], 0
	v_mov_b64_e32 v[10:11], 0
	v_mov_b64_e32 v[12:13], 0
	v_mov_b64_e32 v[14:15], 0
	v_mov_b64_e32 v[16:17], 0
	v_mov_b64_e32 v[18:19], 0
	v_mov_b64_e32 v[20:21], 0
	v_mov_b64_e32 v[22:23], 0
	v_mov_b64_e32 v[24:25], 0
	v_mov_b64_e32 v[26:27], 0
	v_mov_b64_e32 v[28:29], 0
	v_mov_b64_e32 v[30:31], 0
	v_mov_b64_e32 v[32:33], 0
	v_mov_b64_e32 v[34:35], 0
	v_mov_b64_e32 v[36:37], 0
	v_mov_b64_e32 v[38:39], 0
	v_mov_b64_e32 v[40:41], 0
	v_mov_b64_e32 v[42:43], 0
	v_mov_b64_e32 v[44:45], 0
	v_mov_b64_e32 v[46:47], 0
	v_mov_b64_e32 v[48:49], 0
	v_mov_b64_e32 v[50:51], 0
	v_mov_b64_e32 v[52:53], 0
	v_mov_b64_e32 v[54:55], 0
	v_mov_b64_e32 v[56:57], 0
	v_mov_b64_e32 v[58:59], 0
	v_mov_b64_e32 v[60:61], 0
	v_mov_b64_e32 v[62:63], 0
	v_mov_b64_e32 v[64:65], 0
	v_mov_b64_e32 v[66:67], 0
	v_mov_b64_e32 v[68:69], 0
	v_mov_b64_e32 v[70:71], 0
	v_mov_b64_e32 v[72:73], 0
	v_mov_b64_e32 v[74:75], 0
	v_mov_b64_e32 v[76:77], 0
	v_mov_b64_e32 v[78:79], 0
	v_mov_b64_e32 v[80:81], 0
	v_mov_b64_e32 v[82:83], 0
	v_mov_b64_e32 v[84:85], 0
	v_mov_b64_e32 v[86:87], 0
	v_mov_b64_e32 v[88:89], 0
	v_mov_b64_e32 v[90:91], 0
	v_mov_b64_e32 v[92:93], 0
	v_mov_b64_e32 v[94:95], 0
	v_mov_b64_e32 v[96:97], 0
	v_mov_b64_e32 v[98:99], 0
	v_mov_b64_e32 v[100:101], 0
	v_mov_b64_e32 v[102:103], 0
	v_mov_b64_e32 v[104:105], 0
	v_mov_b64_e32 v[106:107], 0
	v_mov_b64_e32 v[108:109], 0
	v_mov_b64_e32 v[110:111], 0
	v_mov_b64_e32 v[112:113], 0
	v_mov_b64_e32 v[114:115], 0
	v_mov_b64_e32 v[116:117], 0
	v_mov_b64_e32 v[118:119], 0
	v_mov_b64_e32 v[120:121], 0
	v_mov_b64_e32 v[122:123], 0
	v_mov_b64_e32 v[124:125], 0
	v_mov_b64_e32 v[126:127], 0

;     DI size_t aoff(const Unit& u, size_t tstep) const { return (size_t)u.pm * tstep; }
;     DI size_t boff(const Unit& u, size_t tstep) const { return (size_t)u.pn * tstep; }
;     DI bool next(int i, Unit& u) const { const long L = (long)i * G + c; if (L >= np) return false; u.pm = pmv; u.pn = (int)(L % nN); u.ks = (int)(L / nN); return true; }
;     DI size_t aoff(const Unit& u, size_t) const { return (size_t)u.ks * kbytes; }
;     DI size_t boff(const Unit& u, size_t tstep) const { return (size_t)u.pn * tstep + (size_t)u.ks * kbytes; }
;     DI bool next(int i, Unit& u) const { Unit t; if (!S.next(i / 3, t)) return false; u.pm = t.pm; u.pn = t.pn; u.ks = i % 3; return true; }
;     DI size_t aoff(const Unit& u, size_t tstep) const { return (u.ks < 2 ? offU : offOA) + (size_t)u.pm * tstep; }
; template <class Epi, class Sched>
; DI void gemm_phase(LAS unsigned char* lds, const Gemm g, const Sched& S, const Epi& E) {
;     ...
;         const bool has_next = S.next(ui + 1, nxt);
;         const char* nA = has_next ? (const char*)g.A + S.aoff(nxt, tstep) : cA; const char* nB = has_next ? (const char*)g.Bt + S.boff(nxt, tstep) : cB;
;         for (int t = 0; t < nt; t += 2) {
;             if constexpr (Epi::HAS_MID) { if (t == E.mid_t(nt)) { int fr3 = fr, fq3 = fq; asm volatile("" : "+v"(fr3), "+v"(fq3)); E.mid(acc, cur, wr, wc, fr3, fq3); } }
;             const bool last = (t == nt - 2);
;             const char* a1 = cA + (size_t)(t + 1) * kstep;
;             const char* a2 = last ? nA : cA + (size_t)(t + 2) * kstep; const char* b2 = last ? nB : cB + (size_t)(t + 2) * kstep;
;             const char* a3 = a2 + kstep; const char* b3 = b2 + kstep;
;     ...
;         for (int a = 0; a < 2; ++a)
; #pragma unroll
;             for (int b = 0; b < 2; ++b)
; #pragma unroll
;                 for (int m = 0; m < 4; ++m)
; #pragma unroll
;                     for (int n = 0; n < 2; ++n) acc[a][b][m][n] = (f32x4){0.f, 0.f, 0.f, 0.f};
.LBB0_1919:
	s_lshl_b32 s1, s1, 8
	s_lshl_b32 s34, s0, 8
	s_or_b32 s35, s1, s58
	s_add_i32 s34, s34, s57
	s_add_u32 s68, s40, 0x100
	v_mov_b32_e32 v0, 0
	v_lshl_add_u64 v[144:145], s[38:39], 0, v[136:137]
	v_lshl_add_u64 v[146:147], s[38:39], 0, v[138:139]
	s_addc_u32 s69, s41, 0
	s_mov_b32 s70, -2
	s_mov_b64 s[8:9], 0
	v_mov_b32_e32 v1, 0
	v_mov_b64_e32 v[2:3], 0
	v_mov_b64_e32 v[4:5], 0
	v_mov_b64_e32 v[6:7], 0
	v_mov_b64_e32 v[8:9], 0
	v_mov_b64_e32 v[10:11], 0
	v_mov_b64_e32 v[12:13], 0
	v_mov_b64_e32 v[14:15], 0
	v_mov_b64_e32 v[16:17], 0
	v_mov_b64_e32 v[18:19], 0
	v_mov_b64_e32 v[20:21], 0
	v_mov_b64_e32 v[22:23], 0
	v_mov_b64_e32 v[24:25], 0
	v_mov_b64_e32 v[26:27], 0
	v_mov_b64_e32 v[28:29], 0
	v_mov_b64_e32 v[30:31], 0
	v_mov_b64_e32 v[32:33], 0
	v_mov_b64_e32 v[34:35], 0
	v_mov_b64_e32 v[36:37], 0
	v_mov_b64_e32 v[38:39], 0
	v_mov_b64_e32 v[40:41], 0
	v_mov_b64_e32 v[42:43], 0
	v_mov_b64_e32 v[44:45], 0
	v_mov_b64_e32 v[46:47], 0
	v_mov_b64_e32 v[48:49], 0
	v_mov_b64_e32 v[50:51], 0
	v_mov_b64_e32 v[52:53], 0
	v_mov_b64_e32 v[54:55], 0
	v_mov_b64_e32 v[56:57], 0
	v_mov_b64_e32 v[58:59], 0
	v_mov_b64_e32 v[60:61], 0
	v_mov_b64_e32 v[62:63], 0
	v_mov_b64_e32 v[64:65], 0
	v_mov_b64_e32 v[66:67], 0
	v_mov_b64_e32 v[68:69], 0
	v_mov_b64_e32 v[70:71], 0
	v_mov_b64_e32 v[72:73], 0
	v_mov_b64_e32 v[74:75], 0
	v_mov_b64_e32 v[76:77], 0
	v_mov_b64_e32 v[78:79], 0
	v_mov_b64_e32 v[80:81], 0
	v_mov_b64_e32 v[82:83], 0
	v_mov_b64_e32 v[84:85], 0
	v_mov_b64_e32 v[86:87], 0
	v_mov_b64_e32 v[88:89], 0
	v_mov_b64_e32 v[90:91], 0
	v_mov_b64_e32 v[92:93], 0
	v_mov_b64_e32 v[94:95], 0
	v_mov_b64_e32 v[96:97], 0
	v_mov_b64_e32 v[98:99], 0
	v_mov_b64_e32 v[100:101], 0
	v_mov_b64_e32 v[102:103], 0
	v_mov_b64_e32 v[104:105], 0
	v_mov_b64_e32 v[106:107], 0
	v_mov_b64_e32 v[108:109], 0
	v_mov_b64_e32 v[110:111], 0
	v_mov_b64_e32 v[112:113], 0
	v_mov_b64_e32 v[114:115], 0
	v_mov_b64_e32 v[116:117], 0
	v_mov_b64_e32 v[118:119], 0
	v_mov_b64_e32 v[120:121], 0
	v_mov_b64_e32 v[122:123], 0
	v_mov_b64_e32 v[124:125], 0
	v_mov_b64_e32 v[126:127], 0
	s_branch .LBB0_1921

; DI u32x4 pack8(f32x4 a, f32x4 b) { u32x4 w; w.x = cvt_pk_bf16(a[0], a[1]); w.y = cvt_pk_bf16(a[2], a[3]); w.z = cvt_pk_bf16(b[0], b[1]); w.w = cvt_pk_bf16(b[2], b[3]); return w; }
;     DI void mid(f32x4 (&acc)[2][2][4][2], const Unit& u, int wr, int wc, int fr, int fq) const {
;         const int col0 = u.pn * 256 + wc * 32 + 8 * fq;
; #pragma unroll
;         for (int ai = 0; ai < 2; ++ai)
; #pragma unroll
;             for (int m = 0; m < 4; ++m) { const size_t off = (size_t)(u.pm * 256 + ai * 128 + wr * 64 + m * 16 + fr) * DM + col0;
; #pragma unroll
;                 for (int bj = 0; bj < 2; ++bj) { *(u32x4*)(Eb + off + bj * 128) = pack8(acc[ai][bj][m][0], acc[ai][bj][m][1]);
;                     acc[ai][bj][m][0] = (f32x4){0.f, 0.f, 0.f, 0.f}; acc[ai][bj][m][1] = (f32x4){0.f, 0.f, 0.f, 0.f}; } }
;     }
.LBB0_1921:
	s_cmpk_lg_i32 s8, 0x200
	s_cbranch_scc1 .LBB0_1920
	v_mov_b32_e32 v148, v194
	v_mov_b32_e32 v149, v192
	v_cvt_pk_bf16_f32 v124, v124, v125
	v_cvt_pk_bf16_f32 v125, v126, v127
	v_cvt_pk_bf16_f32 v126, v120, v121
	v_cvt_pk_bf16_f32 v127, v122, v123
	s_nop 0
	v_add_u32_e32 v148, s34, v148
	v_lshl_add_u32 v150, v149, 3, s35
	v_ashrrev_i32_e32 v149, 31, v148
	v_ashrrev_i32_e32 v151, 31, v150
	v_lshlrev_b64 v[162:163], 12, v[148:149]
	v_lshl_add_u64 v[122:123], s[14:15], 0, v[162:163]
	v_lshlrev_b64 v[120:121], 1, v[150:151]
	v_lshl_add_u64 v[122:123], v[122:123], 0, v[120:121]
	global_store_dwordx4 v[122:123], v[124:127], off
	v_cvt_pk_bf16_f32 v116, v116, v117
	v_cvt_pk_bf16_f32 v117, v118, v119
	v_cvt_pk_bf16_f32 v118, v112, v113
	v_add_u32_e32 v112, 16, v148
	v_ashrrev_i32_e32 v113, 31, v112
	v_lshlrev_b64 v[112:113], 12, v[112:113]
	v_cvt_pk_bf16_f32 v119, v114, v115
	global_store_dwordx4 v[122:123], v[116:119], off offset:256
	v_cvt_pk_bf16_f32 v108, v108, v109
	v_cvt_pk_bf16_f32 v109, v110, v111
	v_cvt_pk_bf16_f32 v110, v104, v105
	v_lshl_add_u64 v[104:105], s[14:15], 0, v[112:113]
	v_lshl_add_u64 v[104:105], v[104:105], 0, v[120:121]
	v_cvt_pk_bf16_f32 v111, v106, v107
	global_store_dwordx4 v[104:105], v[108:111], off
	v_cvt_pk_bf16_f32 v100, v100, v101
	v_cvt_pk_bf16_f32 v101, v102, v103
	v_cvt_pk_bf16_f32 v102, v96, v97
	v_add_u32_e32 v96, 32, v148
	v_ashrrev_i32_e32 v97, 31, v96
	v_lshlrev_b64 v[96:97], 12, v[96:97]
	v_cvt_pk_bf16_f32 v103, v98, v99
	global_store_dwordx4 v[104:105], v[100:103], off offset:256
	v_cvt_pk_bf16_f32 v92, v92, v93
	v_cvt_pk_bf16_f32 v93, v94, v95
	v_cvt_pk_bf16_f32 v94, v88, v89
	v_lshl_add_u64 v[88:89], s[14:15], 0, v[96:97]
	v_lshl_add_u64 v[88:89], v[88:89], 0, v[120:121]
	v_cvt_pk_bf16_f32 v95, v90, v91
	global_store_dwordx4 v[88:89], v[92:95], off
	v_cvt_pk_bf16_f32 v84, v84, v85
	v_cvt_pk_bf16_f32 v85, v86, v87
	v_cvt_pk_bf16_f32 v86, v80, v81
	v_add_u32_e32 v80, 48, v148
	v_ashrrev_i32_e32 v81, 31, v80
	v_lshlrev_b64 v[80:81], 12, v[80:81]
	v_cvt_pk_bf16_f32 v87, v82, v83
	global_store_dwordx4 v[88:89], v[84:87], off offset:256
	v_cvt_pk_bf16_f32 v76, v76, v77
	v_cvt_pk_bf16_f32 v77, v78, v79
	v_cvt_pk_bf16_f32 v78, v72, v73
	v_lshl_add_u64 v[72:73], s[14:15], 0, v[80:81]
	v_lshl_add_u64 v[72:73], v[72:73], 0, v[120:121]
	v_cvt_pk_bf16_f32 v79, v74, v75
	global_store_dwordx4 v[72:73], v[76:79], off
	v_cvt_pk_bf16_f32 v68, v68, v69
	v_cvt_pk_bf16_f32 v69, v70, v71
	v_cvt_pk_bf16_f32 v70, v64, v65
	v_add_u32_e32 v64, 0x80, v148
	v_ashrrev_i32_e32 v65, 31, v64
	v_lshlrev_b64 v[64:65], 12, v[64:65]
	v_cvt_pk_bf16_f32 v71, v66, v67
	global_store_dwordx4 v[72:73], v[68:71], off offset:256
	v_cvt_pk_bf16_f32 v60, v60, v61
	v_cvt_pk_bf16_f32 v61, v62, v63
	v_cvt_pk_bf16_f32 v62, v56, v57
	v_lshl_add_u64 v[56:57], s[14:15], 0, v[64:65]
	v_lshl_add_u64 v[56:57], v[56:57], 0, v[120:121]
	v_cvt_pk_bf16_f32 v63, v58, v59
	global_store_dwordx4 v[56:57], v[60:63], off
	v_cvt_pk_bf16_f32 v52, v52, v53
	v_cvt_pk_bf16_f32 v53, v54, v55
	v_cvt_pk_bf16_f32 v54, v48, v49
	v_add_u32_e32 v48, 0x90, v148
	v_ashrrev_i32_e32 v49, 31, v48
	v_lshlrev_b64 v[48:49], 12, v[48:49]
	v_cvt_pk_bf16_f32 v55, v50, v51
	global_store_dwordx4 v[56:57], v[52:55], off offset:256
	v_cvt_pk_bf16_f32 v44, v44, v45
	v_cvt_pk_bf16_f32 v45, v46, v47
	v_cvt_pk_bf16_f32 v46, v40, v41
	v_lshl_add_u64 v[40:41], s[14:15], 0, v[48:49]
	v_lshl_add_u64 v[40:41], v[40:41], 0, v[120:121]
	v_cvt_pk_bf16_f32 v47, v42, v43
	global_store_dwordx4 v[40:41], v[44:47], off
	v_cvt_pk_bf16_f32 v36, v36, v37
	v_cvt_pk_bf16_f32 v37, v38, v39
	v_cvt_pk_bf16_f32 v38, v32, v33
	v_add_u32_e32 v32, 0xa0, v148
	v_ashrrev_i32_e32 v33, 31, v32
	v_lshlrev_b64 v[32:33], 12, v[32:33]
	v_cvt_pk_bf16_f32 v39, v34, v35
	global_store_dwordx4 v[40:41], v[36:39], off offset:256
	v_cvt_pk_bf16_f32 v28, v28, v29
	v_cvt_pk_bf16_f32 v29, v30, v31
	v_cvt_pk_bf16_f32 v30, v24, v25
	v_lshl_add_u64 v[24:25], s[14:15], 0, v[32:33]
	v_lshl_add_u64 v[24:25], v[24:25], 0, v[120:121]
	v_cvt_pk_bf16_f32 v31, v26, v27
	global_store_dwordx4 v[24:25], v[28:31], off
	v_cvt_pk_bf16_f32 v20, v20, v21
	v_cvt_pk_bf16_f32 v21, v22, v23
	v_cvt_pk_bf16_f32 v22, v16, v17
	v_add_u32_e32 v16, 0xb0, v148
	v_ashrrev_i32_e32 v17, 31, v16
	v_lshlrev_b64 v[16:17], 12, v[16:17]
	v_cvt_pk_bf16_f32 v23, v18, v19
	global_store_dwordx4 v[24:25], v[20:23], off offset:256
	v_cvt_pk_bf16_f32 v12, v12, v13
	v_cvt_pk_bf16_f32 v13, v14, v15
	v_cvt_pk_bf16_f32 v14, v8, v9
	v_lshl_add_u64 v[8:9], s[14:15], 0, v[16:17]
	v_lshl_add_u64 v[8:9], v[8:9], 0, v[120:121]
	v_cvt_pk_bf16_f32 v15, v10, v11
	global_store_dwordx4 v[8:9], v[12:15], off
	v_cvt_pk_bf16_f32 v4, v4, v5
	v_cvt_pk_bf16_f32 v5, v6, v7
	v_cvt_pk_bf16_f32 v6, v0, v1
	v_cvt_pk_bf16_f32 v7, v2, v3
	v_mov_b32_e32 v0, 0
	global_store_dwordx4 v[8:9], v[4:7], off offset:256
	v_mov_b32_e32 v1, 0
	v_mov_b64_e32 v[2:3], 0
	v_mov_b64_e32 v[4:5], 0
	v_mov_b64_e32 v[6:7], 0
	v_mov_b64_e32 v[8:9], 0
	v_mov_b64_e32 v[10:11], 0
	v_mov_b64_e32 v[12:13], 0
	v_mov_b64_e32 v[14:15], 0
	v_mov_b64_e32 v[16:17], 0
	v_mov_b64_e32 v[18:19], 0
	v_mov_b64_e32 v[20:21], 0
	v_mov_b64_e32 v[22:23], 0
	v_mov_b64_e32 v[24:25], 0
	v_mov_b64_e32 v[26:27], 0
	v_mov_b64_e32 v[28:29], 0
	v_mov_b64_e32 v[30:31], 0
	v_mov_b64_e32 v[32:33], 0
	v_mov_b64_e32 v[34:35], 0
	v_mov_b64_e32 v[36:37], 0
	v_mov_b64_e32 v[38:39], 0
	v_mov_b64_e32 v[40:41], 0
	v_mov_b64_e32 v[42:43], 0
	v_mov_b64_e32 v[44:45], 0
	v_mov_b64_e32 v[46:47], 0
	v_mov_b64_e32 v[48:49], 0
	v_mov_b64_e32 v[50:51], 0
	v_mov_b64_e32 v[52:53], 0
	v_mov_b64_e32 v[54:55], 0
	v_mov_b64_e32 v[56:57], 0
	v_mov_b64_e32 v[58:59], 0
	v_mov_b64_e32 v[60:61], 0
	v_mov_b64_e32 v[62:63], 0
	v_mov_b64_e32 v[64:65], 0
	v_mov_b64_e32 v[66:67], 0
	v_mov_b64_e32 v[68:69], 0
	v_mov_b64_e32 v[70:71], 0
	v_mov_b64_e32 v[72:73], 0
	v_mov_b64_e32 v[74:75], 0
	v_mov_b64_e32 v[76:77], 0
	v_mov_b64_e32 v[78:79], 0
	v_mov_b64_e32 v[80:81], 0
	v_mov_b64_e32 v[82:83], 0
	v_mov_b64_e32 v[84:85], 0
	v_mov_b64_e32 v[86:87], 0
	v_mov_b64_e32 v[88:89], 0
	v_mov_b64_e32 v[90:91], 0
	v_mov_b64_e32 v[92:93], 0
	v_mov_b64_e32 v[94:95], 0
	v_mov_b64_e32 v[96:97], 0
	v_mov_b64_e32 v[98:99], 0
	v_mov_b64_e32 v[100:101], 0
	v_mov_b64_e32 v[102:103], 0
	v_mov_b64_e32 v[104:105], 0
	v_mov_b64_e32 v[106:107], 0
	v_mov_b64_e32 v[108:109], 0
	v_mov_b64_e32 v[110:111], 0
	v_mov_b64_e32 v[112:113], 0
	v_mov_b64_e32 v[114:115], 0
	v_mov_b64_e32 v[116:117], 0
	v_mov_b64_e32 v[118:119], 0
	v_mov_b64_e32 v[120:121], 0
	v_mov_b64_e32 v[122:123], 0
	v_mov_b64_e32 v[124:125], 0
	v_mov_b64_e32 v[126:127], 0
	s_branch .LBB0_1920

;     DI size_t aoff(const Unit& u, size_t tstep) const { return (size_t)u.pm * tstep; }
;     DI size_t boff(const Unit& u, size_t tstep) const { return (size_t)u.pn * tstep; }
;     DI bool next(int i, Unit& u) const { Unit t; if (!S.next(i / 3, t)) return false; u.pm = t.pm; u.pn = t.pn; u.ks = i % 3; return true; }
;     DI size_t aoff(const Unit& u, size_t tstep) const { return (u.ks < 2 ? offU : offOA) + (size_t)u.pm * tstep; }
;     DI bool next(int i, Unit& u) const { const long L = (long)i * G + c; if (L >= np) return false; u.pm = pmv; u.pn = (int)(L % nN); u.ks = (int)(L / nN); return true; }
;     DI size_t aoff(const Unit& u, size_t) const { return (size_t)u.ks * kbytes; }
;     DI size_t boff(const Unit& u, size_t tstep) const { return (size_t)u.pn * tstep + (size_t)u.ks * kbytes; }
; template <class Epi, class Sched>
; DI void gemm_phase(LAS unsigned char* lds, const Gemm g, const Sched& S, const Epi& E) {
;     ...
;         for (int a = 0; a < 2; ++a)
; #pragma unroll
;             for (int b = 0; b < 2; ++b)
; #pragma unroll
;                 for (int m = 0; m < 4; ++m)
; #pragma unroll
;                     for (int n = 0; n < 2; ++n) acc[a][b][m][n] = (f32x4){0.f, 0.f, 0.f, 0.f};
.LBB0_1934:
	s_add_u32 s36, s53, s36
	s_addc_u32 s37, s54, s37
	s_and_b64 s[0:1], s[8:9], exec
	v_mov_b32_e32 v0, 0
	s_cselect_b32 s15, s37, s19
	s_cselect_b32 s29, s36, s18
	s_mov_b32 s0, 0
	s_mov_b64 s[8:9], -1
	s_mov_b64 s[38:39], 0
	v_mov_b32_e32 v1, 0
	v_mov_b64_e32 v[2:3], 0
	v_mov_b64_e32 v[4:5], 0
	v_mov_b64_e32 v[6:7], 0
	v_mov_b64_e32 v[8:9], 0
	v_mov_b64_e32 v[10:11], 0
	v_mov_b64_e32 v[12:13], 0
	v_mov_b64_e32 v[14:15], 0
	v_mov_b64_e32 v[16:17], 0
	v_mov_b64_e32 v[18:19], 0
	v_mov_b64_e32 v[20:21], 0
	v_mov_b64_e32 v[22:23], 0
	v_mov_b64_e32 v[24:25], 0
	v_mov_b64_e32 v[26:27], 0
	v_mov_b64_e32 v[28:29], 0
	v_mov_b64_e32 v[30:31], 0
	v_mov_b64_e32 v[32:33], 0
	v_mov_b64_e32 v[34:35], 0
	v_mov_b64_e32 v[36:37], 0
	v_mov_b64_e32 v[38:39], 0
	v_mov_b64_e32 v[40:41], 0
	v_mov_b64_e32 v[42:43], 0
	v_mov_b64_e32 v[44:45], 0
	v_mov_b64_e32 v[46:47], 0
	v_mov_b64_e32 v[48:49], 0
	v_mov_b64_e32 v[50:51], 0
	v_mov_b64_e32 v[52:53], 0
	v_mov_b64_e32 v[54:55], 0
	v_mov_b64_e32 v[56:57], 0
	v_mov_b64_e32 v[58:59], 0
	v_mov_b64_e32 v[60:61], 0
	v_mov_b64_e32 v[62:63], 0
	v_mov_b64_e32 v[64:65], 0
	v_mov_b64_e32 v[66:67], 0
	v_mov_b64_e32 v[68:69], 0
	v_mov_b64_e32 v[70:71], 0
	v_mov_b64_e32 v[72:73], 0
	v_mov_b64_e32 v[74:75], 0
	v_mov_b64_e32 v[76:77], 0
	v_mov_b64_e32 v[78:79], 0
	v_mov_b64_e32 v[80:81], 0
	v_mov_b64_e32 v[82:83], 0
	v_mov_b64_e32 v[84:85], 0
	v_mov_b64_e32 v[86:87], 0
	v_mov_b64_e32 v[88:89], 0
	v_mov_b64_e32 v[90:91], 0
	v_mov_b64_e32 v[92:93], 0
	v_mov_b64_e32 v[94:95], 0
	v_mov_b64_e32 v[96:97], 0
	v_mov_b64_e32 v[98:99], 0
	v_mov_b64_e32 v[100:101], 0
	v_mov_b64_e32 v[102:103], 0
	v_mov_b64_e32 v[104:105], 0
	v_mov_b64_e32 v[106:107], 0
	v_mov_b64_e32 v[108:109], 0
	v_mov_b64_e32 v[110:111], 0
	v_mov_b64_e32 v[112:113], 0
	v_mov_b64_e32 v[114:115], 0
	v_mov_b64_e32 v[116:117], 0
	v_mov_b64_e32 v[118:119], 0
	v_mov_b64_e32 v[120:121], 0
	v_mov_b64_e32 v[122:123], 0
	v_mov_b64_e32 v[124:125], 0
	v_mov_b64_e32 v[126:127], 0
